# v66 + GEMM K-loop edge: counter/pointer updates and loop test moved in front of the closing barrier (6 K-loops)
# baseline (speedup 1.0000x reference)
.LBB0_162:
	ds_read_b128 v[154:157], v151
	ds_read_b128 v[158:161], v151 offset:1024
	ds_read_b128 v[162:165], v151 offset:2048
	ds_read_b128 v[166:169], v151 offset:3072
	ds_read_b128 v[170:173], v152
	ds_read_b128 v[174:177], v152 offset:1024
	ds_read_b128 v[178:181], v152 offset:2048
	ds_read_b128 v[182:185], v152 offset:3072
	s_add_u32 s58, s40, 0xfff00080
	s_addc_u32 s59, s41, -1
	s_cmp_eq_u32 s73, 60
	s_cselect_b32 s63, s25, s59
	s_cselect_b32 s62, s67, s58
	s_cselect_b32 s59, s23, s72
	s_cselect_b32 s58, s70, s71
	v_lshl_add_u64 v[146:147], s[40:41], 0, v[138:139]
	s_add_i32 m0, s42, 0xc000
	ds_read_b128 v[186:189], v153
	ds_read_b128 v[190:193], v153 offset:1024
	ds_read_b128 v[194:197], v153 offset:2048
	ds_read_b128 v[198:201], v153 offset:3072
	ds_read_b128 v[202:205], v153 offset:4096
	ds_read_b128 v[206:209], v153 offset:5120
	ds_read_b128 v[210:213], v153 offset:6144
	ds_read_b128 v[214:217], v153 offset:7168
	global_load_lds_dwordx4 v[146:147], off
	v_lshl_add_u64 v[146:147], s[40:41], 0, v[140:141]
	s_add_i32 m0, s42, 0xe000
	s_nop 0
	global_load_lds_dwordx4 v[146:147], off
	s_waitcnt vmcnt(8)
	s_waitcnt lgkmcnt(0)
	s_barrier
	s_setprio 1
	s_waitcnt lgkmcnt(0)
	v_mfma_f32_16x16x32_bf16 v[126:129], v[154:157], v[186:189], v[126:129]
	v_mfma_f32_16x16x32_bf16 v[118:121], v[162:165], v[186:189], v[118:121]
	v_mfma_f32_16x16x32_bf16 v[110:113], v[154:157], v[194:197], v[110:113]
	v_mfma_f32_16x16x32_bf16 v[102:105], v[162:165], v[194:197], v[102:105]
	v_mfma_f32_16x16x32_bf16 v[94:97], v[154:157], v[202:205], v[94:97]
	v_mfma_f32_16x16x32_bf16 v[86:89], v[162:165], v[202:205], v[86:89]
	v_mfma_f32_16x16x32_bf16 v[78:81], v[154:157], v[210:213], v[78:81]
	v_mfma_f32_16x16x32_bf16 v[70:73], v[162:165], v[210:213], v[70:73]
	v_mfma_f32_16x16x32_bf16 v[126:129], v[158:161], v[190:193], v[126:129]
	v_mfma_f32_16x16x32_bf16 v[118:121], v[166:169], v[190:193], v[118:121]
	v_mfma_f32_16x16x32_bf16 v[110:113], v[158:161], v[198:201], v[110:113]
	v_mfma_f32_16x16x32_bf16 v[102:105], v[166:169], v[198:201], v[102:105]
	v_mfma_f32_16x16x32_bf16 v[94:97], v[158:161], v[206:209], v[94:97]
	v_mfma_f32_16x16x32_bf16 v[86:89], v[166:169], v[206:209], v[86:89]
	v_mfma_f32_16x16x32_bf16 v[78:81], v[158:161], v[214:217], v[78:81]
	v_mfma_f32_16x16x32_bf16 v[70:73], v[166:169], v[214:217], v[70:73]
	s_setprio 0
	s_setprio 1
	v_mfma_f32_16x16x32_bf16 v[122:125], v[170:173], v[186:189], v[122:125]
	v_mfma_f32_16x16x32_bf16 v[114:117], v[178:181], v[186:189], v[114:117]
	v_mfma_f32_16x16x32_bf16 v[106:109], v[170:173], v[194:197], v[106:109]
	v_mfma_f32_16x16x32_bf16 v[98:101], v[178:181], v[194:197], v[98:101]
	v_mfma_f32_16x16x32_bf16 v[90:93], v[170:173], v[202:205], v[90:93]
	v_mfma_f32_16x16x32_bf16 v[82:85], v[178:181], v[202:205], v[82:85]
	v_mfma_f32_16x16x32_bf16 v[74:77], v[170:173], v[210:213], v[74:77]
	v_mfma_f32_16x16x32_bf16 v[66:69], v[178:181], v[210:213], v[66:69]
	v_mfma_f32_16x16x32_bf16 v[122:125], v[174:177], v[190:193], v[122:125]
	v_mfma_f32_16x16x32_bf16 v[114:117], v[182:185], v[190:193], v[114:117]
	v_mfma_f32_16x16x32_bf16 v[106:109], v[174:177], v[198:201], v[106:109]
	v_mfma_f32_16x16x32_bf16 v[98:101], v[182:185], v[198:201], v[98:101]
	v_mfma_f32_16x16x32_bf16 v[90:93], v[174:177], v[206:209], v[90:93]
	v_mfma_f32_16x16x32_bf16 v[82:85], v[182:185], v[206:209], v[82:85]
	v_mfma_f32_16x16x32_bf16 v[74:77], v[174:177], v[214:217], v[74:77]
	v_mfma_f32_16x16x32_bf16 v[66:69], v[182:185], v[214:217], v[66:69]
	s_setprio 0
	s_barrier
	s_add_i32 s74, s50, s15
	v_lshl_add_u64 v[146:147], s[58:59], 0, v[134:135]
	s_mov_b32 m0, s74
	ds_read_b128 v[186:189], v153 offset:16384
	ds_read_b128 v[190:193], v153 offset:17408
	ds_read_b128 v[194:197], v153 offset:18432
	ds_read_b128 v[198:201], v153 offset:19456
	ds_read_b128 v[202:205], v153 offset:20480
	ds_read_b128 v[206:209], v153 offset:21504
	ds_read_b128 v[210:213], v153 offset:22528
	ds_read_b128 v[214:217], v153 offset:23552
	global_load_lds_dwordx4 v[146:147], off
	s_add_i32 m0, s74, 0x2000
	s_add_u32 s74, s58, 0x100000
	v_lshl_add_u64 v[218:219], s[58:59], 0, v[130:131]
	s_addc_u32 s75, s59, 0
	s_add_i32 s82, s51, s15
	global_load_lds_dwordx4 v[218:219], off
	v_lshl_add_u64 v[220:221], s[74:75], 0, v[134:135]
	s_mov_b32 m0, s82
	v_lshl_add_u64 v[222:223], s[62:63], 0, v[132:133]
	global_load_lds_dwordx4 v[220:221], off
	v_lshl_add_u64 v[220:221], s[74:75], 0, v[130:131]
	s_add_i32 m0, s82, 0x2000
	s_nop 0
	global_load_lds_dwordx4 v[220:221], off
	v_lshl_add_u64 v[220:221], s[62:63], 0, v[136:137]
	s_mov_b32 m0, s42
	s_nop 0
	global_load_lds_dwordx4 v[220:221], off
	s_mov_b32 m0, s43
	s_nop 0
	global_load_lds_dwordx4 v[222:223], off
	s_waitcnt vmcnt(8)
	s_waitcnt lgkmcnt(0)
	s_barrier
	s_setprio 1
	s_waitcnt lgkmcnt(0)
	v_mfma_f32_16x16x32_bf16 v[62:65], v[154:157], v[186:189], v[62:65]
	v_mfma_f32_16x16x32_bf16 v[54:57], v[162:165], v[186:189], v[54:57]
	v_mfma_f32_16x16x32_bf16 v[46:49], v[154:157], v[194:197], v[46:49]
	v_mfma_f32_16x16x32_bf16 v[38:41], v[162:165], v[194:197], v[38:41]
	v_mfma_f32_16x16x32_bf16 v[30:33], v[154:157], v[202:205], v[30:33]
	v_mfma_f32_16x16x32_bf16 v[22:25], v[162:165], v[202:205], v[22:25]
	v_mfma_f32_16x16x32_bf16 v[14:17], v[154:157], v[210:213], v[14:17]
	v_mfma_f32_16x16x32_bf16 v[6:9], v[162:165], v[210:213], v[6:9]
	v_mfma_f32_16x16x32_bf16 v[62:65], v[158:161], v[190:193], v[62:65]
	v_mfma_f32_16x16x32_bf16 v[54:57], v[166:169], v[190:193], v[54:57]
	v_mfma_f32_16x16x32_bf16 v[46:49], v[158:161], v[198:201], v[46:49]
	v_mfma_f32_16x16x32_bf16 v[38:41], v[166:169], v[198:201], v[38:41]
	v_mfma_f32_16x16x32_bf16 v[30:33], v[158:161], v[206:209], v[30:33]
	v_mfma_f32_16x16x32_bf16 v[22:25], v[166:169], v[206:209], v[22:25]
	v_mfma_f32_16x16x32_bf16 v[14:17], v[158:161], v[214:217], v[14:17]
	v_mfma_f32_16x16x32_bf16 v[6:9], v[166:169], v[214:217], v[6:9]
	s_setprio 0
	s_setprio 1
	v_mfma_f32_16x16x32_bf16 v[58:61], v[170:173], v[186:189], v[58:61]
	v_mfma_f32_16x16x32_bf16 v[50:53], v[178:181], v[186:189], v[50:53]
	v_mfma_f32_16x16x32_bf16 v[42:45], v[170:173], v[194:197], v[42:45]
	v_mfma_f32_16x16x32_bf16 v[34:37], v[178:181], v[194:197], v[34:37]
	v_mfma_f32_16x16x32_bf16 v[26:29], v[170:173], v[202:205], v[26:29]
	v_mfma_f32_16x16x32_bf16 v[18:21], v[178:181], v[202:205], v[18:21]
	v_mfma_f32_16x16x32_bf16 v[10:13], v[170:173], v[210:213], v[10:13]
	v_mfma_f32_16x16x32_bf16 v[2:5], v[178:181], v[210:213], v[2:5]
	v_mfma_f32_16x16x32_bf16 v[58:61], v[174:177], v[190:193], v[58:61]
	v_mfma_f32_16x16x32_bf16 v[50:53], v[182:185], v[190:193], v[50:53]
	v_mfma_f32_16x16x32_bf16 v[42:45], v[174:177], v[198:201], v[42:45]
	v_mfma_f32_16x16x32_bf16 v[34:37], v[182:185], v[198:201], v[34:37]
	v_mfma_f32_16x16x32_bf16 v[26:29], v[174:177], v[206:209], v[26:29]
	v_mfma_f32_16x16x32_bf16 v[18:21], v[182:185], v[206:209], v[18:21]
	v_mfma_f32_16x16x32_bf16 v[10:13], v[174:177], v[214:217], v[10:13]
	v_mfma_f32_16x16x32_bf16 v[2:5], v[182:185], v[214:217], v[2:5]
	s_setprio 0
	s_barrier
	s_add_i32 s74, 0, 0x18000
	s_add_i32 s75, 0, 0x1c000
	v_add_u32_e32 v166, s74, v149
	v_add_u32_e32 v182, s75, v149
	ds_read_b128 v[154:157], v166
	ds_read_b128 v[158:161], v166 offset:1024
	ds_read_b128 v[162:165], v166 offset:2048
	ds_read_b128 v[166:169], v166 offset:3072
	ds_read_b128 v[170:173], v182
	ds_read_b128 v[174:177], v182 offset:1024
	ds_read_b128 v[178:181], v182 offset:2048
	ds_read_b128 v[182:185], v182 offset:3072
	s_add_u32 s62, s62, 0x100000
	s_addc_u32 s63, s63, 0
	s_mov_b32 m0, s44
	v_lshl_add_u64 v[224:225], s[62:63], 0, v[136:137]
	ds_read_b128 v[186:189], v153 offset:32768
	ds_read_b128 v[190:193], v153 offset:33792
	ds_read_b128 v[194:197], v153 offset:34816
	ds_read_b128 v[198:201], v153 offset:35840
	ds_read_b128 v[202:205], v153 offset:36864
	ds_read_b128 v[206:209], v153 offset:37888
	ds_read_b128 v[210:213], v153 offset:38912
	ds_read_b128 v[214:217], v153 offset:39936
	global_load_lds_dwordx4 v[224:225], off
	v_lshl_add_u64 v[224:225], s[62:63], 0, v[132:133]
	s_mov_b32 m0, s45
	s_nop 0
	global_load_lds_dwordx4 v[224:225], off
	s_waitcnt vmcnt(8)
	s_waitcnt lgkmcnt(0)
	s_barrier
	s_setprio 1
	s_waitcnt lgkmcnt(0)
	v_mfma_f32_16x16x32_bf16 v[126:129], v[154:157], v[186:189], v[126:129]
	v_mfma_f32_16x16x32_bf16 v[118:121], v[162:165], v[186:189], v[118:121]
	v_mfma_f32_16x16x32_bf16 v[110:113], v[154:157], v[194:197], v[110:113]
	v_mfma_f32_16x16x32_bf16 v[102:105], v[162:165], v[194:197], v[102:105]
	v_mfma_f32_16x16x32_bf16 v[94:97], v[154:157], v[202:205], v[94:97]
	v_mfma_f32_16x16x32_bf16 v[86:89], v[162:165], v[202:205], v[86:89]
	v_mfma_f32_16x16x32_bf16 v[78:81], v[154:157], v[210:213], v[78:81]
	v_mfma_f32_16x16x32_bf16 v[70:73], v[162:165], v[210:213], v[70:73]
	v_mfma_f32_16x16x32_bf16 v[126:129], v[158:161], v[190:193], v[126:129]
	v_mfma_f32_16x16x32_bf16 v[118:121], v[166:169], v[190:193], v[118:121]
	v_mfma_f32_16x16x32_bf16 v[110:113], v[158:161], v[198:201], v[110:113]
	v_mfma_f32_16x16x32_bf16 v[102:105], v[166:169], v[198:201], v[102:105]
	v_mfma_f32_16x16x32_bf16 v[94:97], v[158:161], v[206:209], v[94:97]
	v_mfma_f32_16x16x32_bf16 v[86:89], v[166:169], v[206:209], v[86:89]
	v_mfma_f32_16x16x32_bf16 v[78:81], v[158:161], v[214:217], v[78:81]
	v_mfma_f32_16x16x32_bf16 v[70:73], v[166:169], v[214:217], v[70:73]
	s_setprio 0
	s_setprio 1
	v_mfma_f32_16x16x32_bf16 v[122:125], v[170:173], v[186:189], v[122:125]
	v_mfma_f32_16x16x32_bf16 v[114:117], v[178:181], v[186:189], v[114:117]
	v_mfma_f32_16x16x32_bf16 v[106:109], v[170:173], v[194:197], v[106:109]
	v_mfma_f32_16x16x32_bf16 v[98:101], v[178:181], v[194:197], v[98:101]
	v_mfma_f32_16x16x32_bf16 v[90:93], v[170:173], v[202:205], v[90:93]
	v_mfma_f32_16x16x32_bf16 v[82:85], v[178:181], v[202:205], v[82:85]
	v_mfma_f32_16x16x32_bf16 v[74:77], v[170:173], v[210:213], v[74:77]
	v_mfma_f32_16x16x32_bf16 v[66:69], v[178:181], v[210:213], v[66:69]
	v_mfma_f32_16x16x32_bf16 v[122:125], v[174:177], v[190:193], v[122:125]
	v_mfma_f32_16x16x32_bf16 v[114:117], v[182:185], v[190:193], v[114:117]
	v_mfma_f32_16x16x32_bf16 v[106:109], v[174:177], v[198:201], v[106:109]
	v_mfma_f32_16x16x32_bf16 v[98:101], v[182:185], v[198:201], v[98:101]
	v_mfma_f32_16x16x32_bf16 v[90:93], v[174:177], v[206:209], v[90:93]
	v_mfma_f32_16x16x32_bf16 v[82:85], v[182:185], v[206:209], v[82:85]
	v_mfma_f32_16x16x32_bf16 v[74:77], v[174:177], v[214:217], v[74:77]
	v_mfma_f32_16x16x32_bf16 v[66:69], v[182:185], v[214:217], v[66:69]
	s_setprio 0
	s_barrier
	s_add_i32 s62, s74, s15
	v_lshl_add_u64 v[146:147], v[146:147], 0, s[10:11]
	s_mov_b32 m0, s62
	ds_read_b128 v[186:189], v153 offset:49152
	ds_read_b128 v[190:193], v153 offset:50176
	ds_read_b128 v[194:197], v153 offset:51200
	ds_read_b128 v[198:201], v153 offset:52224
	ds_read_b128 v[202:205], v153 offset:53248
	ds_read_b128 v[206:209], v153 offset:54272
	ds_read_b128 v[210:213], v153 offset:55296
	ds_read_b128 v[214:217], v153 offset:56320
	global_load_lds_dwordx4 v[146:147], off
	s_add_i32 m0, s62, 0x2000
	s_add_u32 s58, s58, 0x100080
	v_lshl_add_u64 v[146:147], v[218:219], 0, s[10:11]
	s_addc_u32 s59, s59, 0
	s_add_i32 s62, s75, s15
	global_load_lds_dwordx4 v[146:147], off
	v_lshl_add_u64 v[146:147], s[58:59], 0, v[134:135]
	s_mov_b32 m0, s62
	s_nop 0
	global_load_lds_dwordx4 v[146:147], off
	v_lshl_add_u64 v[146:147], s[58:59], 0, v[130:131]
	s_add_i32 m0, s62, 0x2000
	s_nop 0
	global_load_lds_dwordx4 v[146:147], off
	v_lshl_add_u64 v[146:147], v[220:221], 0, s[10:11]
	s_mov_b32 m0, s47
	s_nop 0
	global_load_lds_dwordx4 v[146:147], off
	v_lshl_add_u64 v[146:147], v[222:223], 0, s[10:11]
	s_mov_b32 m0, s48
	s_nop 0
	global_load_lds_dwordx4 v[146:147], off
	s_waitcnt vmcnt(8)
	s_waitcnt lgkmcnt(0)
	s_barrier
	s_setprio 1
	s_waitcnt lgkmcnt(0)
	v_mfma_f32_16x16x32_bf16 v[62:65], v[154:157], v[186:189], v[62:65]
	v_mfma_f32_16x16x32_bf16 v[54:57], v[162:165], v[186:189], v[54:57]
	v_mfma_f32_16x16x32_bf16 v[46:49], v[154:157], v[194:197], v[46:49]
	v_mfma_f32_16x16x32_bf16 v[38:41], v[162:165], v[194:197], v[38:41]
	v_mfma_f32_16x16x32_bf16 v[30:33], v[154:157], v[202:205], v[30:33]
	v_mfma_f32_16x16x32_bf16 v[22:25], v[162:165], v[202:205], v[22:25]
	v_mfma_f32_16x16x32_bf16 v[14:17], v[154:157], v[210:213], v[14:17]
	v_mfma_f32_16x16x32_bf16 v[6:9], v[162:165], v[210:213], v[6:9]
	v_mfma_f32_16x16x32_bf16 v[62:65], v[158:161], v[190:193], v[62:65]
	v_mfma_f32_16x16x32_bf16 v[54:57], v[166:169], v[190:193], v[54:57]
	v_mfma_f32_16x16x32_bf16 v[46:49], v[158:161], v[198:201], v[46:49]
	v_mfma_f32_16x16x32_bf16 v[38:41], v[166:169], v[198:201], v[38:41]
	v_mfma_f32_16x16x32_bf16 v[30:33], v[158:161], v[206:209], v[30:33]
	v_mfma_f32_16x16x32_bf16 v[22:25], v[166:169], v[206:209], v[22:25]
	v_mfma_f32_16x16x32_bf16 v[14:17], v[158:161], v[214:217], v[14:17]
	v_mfma_f32_16x16x32_bf16 v[6:9], v[166:169], v[214:217], v[6:9]
	s_setprio 0
	s_setprio 1
	v_mfma_f32_16x16x32_bf16 v[58:61], v[170:173], v[186:189], v[58:61]
	v_mfma_f32_16x16x32_bf16 v[50:53], v[178:181], v[186:189], v[50:53]
	v_mfma_f32_16x16x32_bf16 v[42:45], v[170:173], v[194:197], v[42:45]
	v_mfma_f32_16x16x32_bf16 v[34:37], v[178:181], v[194:197], v[34:37]
	v_mfma_f32_16x16x32_bf16 v[26:29], v[170:173], v[202:205], v[26:29]
	v_mfma_f32_16x16x32_bf16 v[18:21], v[178:181], v[202:205], v[18:21]
	v_mfma_f32_16x16x32_bf16 v[10:13], v[170:173], v[210:213], v[10:13]
	v_mfma_f32_16x16x32_bf16 v[2:5], v[178:181], v[210:213], v[2:5]
	v_mfma_f32_16x16x32_bf16 v[58:61], v[174:177], v[190:193], v[58:61]
	v_mfma_f32_16x16x32_bf16 v[50:53], v[182:185], v[190:193], v[50:53]
	v_mfma_f32_16x16x32_bf16 v[42:45], v[174:177], v[198:201], v[42:45]
	v_mfma_f32_16x16x32_bf16 v[34:37], v[182:185], v[198:201], v[34:37]
	v_mfma_f32_16x16x32_bf16 v[26:29], v[174:177], v[206:209], v[26:29]
	v_mfma_f32_16x16x32_bf16 v[18:21], v[182:185], v[206:209], v[18:21]
	v_mfma_f32_16x16x32_bf16 v[10:13], v[174:177], v[214:217], v[10:13]
	v_mfma_f32_16x16x32_bf16 v[2:5], v[182:185], v[214:217], v[2:5]
	s_add_i32 s73, s73, 2
	s_add_u32 s40, s40, 0x100
	s_addc_u32 s41, s41, 0
	s_add_u32 s71, s71, 0x100
	s_addc_u32 s72, s72, 0
	s_cmp_gt_u32 s73, 61
	s_setprio 0
	s_barrier
	s_cbranch_scc0 .LBB0_162
	s_and_b64 vcc, exec, s[12:13]
	s_cbranch_vccz .LBB0_165
	s_barrier

.LBB0_260:
	ds_read_b128 v[154:157], v150
	ds_read_b128 v[158:161], v150 offset:1024
	ds_read_b128 v[162:165], v150 offset:2048
	ds_read_b128 v[166:169], v150 offset:3072
	ds_read_b128 v[170:173], v151
	ds_read_b128 v[174:177], v151 offset:1024
	ds_read_b128 v[178:181], v151 offset:2048
	ds_read_b128 v[182:185], v151 offset:3072
	s_add_u32 s30, s28, 0x100
	s_addc_u32 s31, s29, 0
	s_cmpk_eq_i32 s74, 0xa8
	s_cselect_b32 s63, s5, s31
	s_cselect_b32 s62, s4, s30
	s_cselect_b32 s41, s27, s73
	s_cselect_b32 s40, s26, s72
	v_lshl_add_u64 v[146:147], s[28:29], 0, v[138:139]
	s_add_i32 m0, s15, 0xc000
	ds_read_b128 v[186:189], v152
	ds_read_b128 v[190:193], v152 offset:1024
	ds_read_b128 v[194:197], v152 offset:2048
	ds_read_b128 v[198:201], v152 offset:3072
	ds_read_b128 v[202:205], v152 offset:4096
	ds_read_b128 v[206:209], v152 offset:5120
	ds_read_b128 v[210:213], v152 offset:6144
	ds_read_b128 v[214:217], v152 offset:7168
	global_load_lds_dwordx4 v[146:147], off
	v_lshl_add_u64 v[146:147], s[28:29], 0, v[140:141]
	s_add_i32 m0, s15, 0xe000
	s_nop 0
	global_load_lds_dwordx4 v[146:147], off
	s_waitcnt vmcnt(8)
	s_waitcnt lgkmcnt(0)
	s_barrier
	s_setprio 1
	s_waitcnt lgkmcnt(0)
	v_mfma_f32_16x16x32_bf16 v[126:129], v[154:157], v[186:189], v[126:129]
	v_mfma_f32_16x16x32_bf16 v[122:125], v[162:165], v[186:189], v[122:125]
	v_mfma_f32_16x16x32_bf16 v[118:121], v[154:157], v[194:197], v[118:121]
	v_mfma_f32_16x16x32_bf16 v[110:113], v[162:165], v[194:197], v[110:113]
	v_mfma_f32_16x16x32_bf16 v[102:105], v[154:157], v[202:205], v[102:105]
	v_mfma_f32_16x16x32_bf16 v[94:97], v[162:165], v[202:205], v[94:97]
	v_mfma_f32_16x16x32_bf16 v[82:85], v[154:157], v[210:213], v[82:85]
	v_mfma_f32_16x16x32_bf16 v[74:77], v[162:165], v[210:213], v[74:77]
	v_mfma_f32_16x16x32_bf16 v[126:129], v[158:161], v[190:193], v[126:129]
	v_mfma_f32_16x16x32_bf16 v[122:125], v[166:169], v[190:193], v[122:125]
	v_mfma_f32_16x16x32_bf16 v[118:121], v[158:161], v[198:201], v[118:121]
	v_mfma_f32_16x16x32_bf16 v[110:113], v[166:169], v[198:201], v[110:113]
	v_mfma_f32_16x16x32_bf16 v[102:105], v[158:161], v[206:209], v[102:105]
	v_mfma_f32_16x16x32_bf16 v[94:97], v[166:169], v[206:209], v[94:97]
	v_mfma_f32_16x16x32_bf16 v[82:85], v[158:161], v[214:217], v[82:85]
	v_mfma_f32_16x16x32_bf16 v[74:77], v[166:169], v[214:217], v[74:77]
	s_setprio 0
	s_setprio 1
	v_mfma_f32_16x16x32_bf16 v[114:117], v[170:173], v[186:189], v[114:117]
	v_mfma_f32_16x16x32_bf16 v[106:109], v[178:181], v[186:189], v[106:109]
	v_mfma_f32_16x16x32_bf16 v[98:101], v[170:173], v[194:197], v[98:101]
	v_mfma_f32_16x16x32_bf16 v[90:93], v[178:181], v[194:197], v[90:93]
	v_mfma_f32_16x16x32_bf16 v[86:89], v[170:173], v[202:205], v[86:89]
	v_mfma_f32_16x16x32_bf16 v[78:81], v[178:181], v[202:205], v[78:81]
	v_mfma_f32_16x16x32_bf16 v[70:73], v[170:173], v[210:213], v[70:73]
	v_mfma_f32_16x16x32_bf16 v[66:69], v[178:181], v[210:213], v[66:69]
	v_mfma_f32_16x16x32_bf16 v[114:117], v[174:177], v[190:193], v[114:117]
	v_mfma_f32_16x16x32_bf16 v[106:109], v[182:185], v[190:193], v[106:109]
	v_mfma_f32_16x16x32_bf16 v[98:101], v[174:177], v[198:201], v[98:101]
	v_mfma_f32_16x16x32_bf16 v[90:93], v[182:185], v[198:201], v[90:93]
	v_mfma_f32_16x16x32_bf16 v[86:89], v[174:177], v[206:209], v[86:89]
	v_mfma_f32_16x16x32_bf16 v[78:81], v[182:185], v[206:209], v[78:81]
	v_mfma_f32_16x16x32_bf16 v[70:73], v[174:177], v[214:217], v[70:73]
	v_mfma_f32_16x16x32_bf16 v[66:69], v[182:185], v[214:217], v[66:69]
	s_setprio 0
	s_barrier
	s_add_i32 s28, s50, s3
	v_lshl_add_u64 v[146:147], s[40:41], 0, v[132:133]
	s_mov_b32 m0, s28
	ds_read_b128 v[186:189], v152 offset:16384
	ds_read_b128 v[190:193], v152 offset:17408
	ds_read_b128 v[194:197], v152 offset:18432
	ds_read_b128 v[198:201], v152 offset:19456
	ds_read_b128 v[202:205], v152 offset:20480
	ds_read_b128 v[206:209], v152 offset:21504
	ds_read_b128 v[210:213], v152 offset:22528
	ds_read_b128 v[214:217], v152 offset:23552
	global_load_lds_dwordx4 v[146:147], off
	s_add_i32 m0, s28, 0x2000
	s_add_u32 s28, s40, 0x2b0000
	v_lshl_add_u64 v[218:219], s[40:41], 0, v[136:137]
	s_addc_u32 s29, s41, 0
	s_add_i32 s75, s51, s3
	global_load_lds_dwordx4 v[218:219], off
	v_lshl_add_u64 v[220:221], s[28:29], 0, v[132:133]
	s_mov_b32 m0, s75
	v_lshl_add_u64 v[222:223], s[62:63], 0, v[134:135]
	global_load_lds_dwordx4 v[220:221], off
	v_lshl_add_u64 v[220:221], s[28:29], 0, v[136:137]
	s_add_i32 m0, s75, 0x2000
	s_nop 0
	global_load_lds_dwordx4 v[220:221], off
	v_lshl_add_u64 v[220:221], s[62:63], 0, v[130:131]
	s_mov_b32 m0, s15
	s_nop 0
	global_load_lds_dwordx4 v[220:221], off
	s_mov_b32 m0, s36
	s_nop 0
	global_load_lds_dwordx4 v[222:223], off
	s_waitcnt vmcnt(8)
	s_waitcnt lgkmcnt(0)
	s_barrier
	s_setprio 1
	s_waitcnt lgkmcnt(0)
	v_mfma_f32_16x16x32_bf16 v[62:65], v[154:157], v[186:189], v[62:65]
	v_mfma_f32_16x16x32_bf16 v[58:61], v[162:165], v[186:189], v[58:61]
	v_mfma_f32_16x16x32_bf16 v[54:57], v[154:157], v[194:197], v[54:57]
	v_mfma_f32_16x16x32_bf16 v[46:49], v[162:165], v[194:197], v[46:49]
	v_mfma_f32_16x16x32_bf16 v[38:41], v[154:157], v[202:205], v[38:41]
	v_mfma_f32_16x16x32_bf16 v[30:33], v[162:165], v[202:205], v[30:33]
	v_mfma_f32_16x16x32_bf16 v[22:25], v[154:157], v[210:213], v[22:25]
	v_mfma_f32_16x16x32_bf16 v[14:17], v[162:165], v[210:213], v[14:17]
	v_mfma_f32_16x16x32_bf16 v[62:65], v[158:161], v[190:193], v[62:65]
	v_mfma_f32_16x16x32_bf16 v[58:61], v[166:169], v[190:193], v[58:61]
	v_mfma_f32_16x16x32_bf16 v[54:57], v[158:161], v[198:201], v[54:57]
	v_mfma_f32_16x16x32_bf16 v[46:49], v[166:169], v[198:201], v[46:49]
	v_mfma_f32_16x16x32_bf16 v[38:41], v[158:161], v[206:209], v[38:41]
	v_mfma_f32_16x16x32_bf16 v[30:33], v[166:169], v[206:209], v[30:33]
	v_mfma_f32_16x16x32_bf16 v[22:25], v[158:161], v[214:217], v[22:25]
	v_mfma_f32_16x16x32_bf16 v[14:17], v[166:169], v[214:217], v[14:17]
	s_setprio 0
	s_setprio 1
	v_mfma_f32_16x16x32_bf16 v[50:53], v[170:173], v[186:189], v[50:53]
	v_mfma_f32_16x16x32_bf16 v[42:45], v[178:181], v[186:189], v[42:45]
	v_mfma_f32_16x16x32_bf16 v[34:37], v[170:173], v[194:197], v[34:37]
	v_mfma_f32_16x16x32_bf16 v[26:29], v[178:181], v[194:197], v[26:29]
	v_mfma_f32_16x16x32_bf16 v[18:21], v[170:173], v[202:205], v[18:21]
	v_mfma_f32_16x16x32_bf16 v[10:13], v[178:181], v[202:205], v[10:13]
	v_mfma_f32_16x16x32_bf16 v[6:9], v[170:173], v[210:213], v[6:9]
	v_mfma_f32_16x16x32_bf16 v[2:5], v[178:181], v[210:213], v[2:5]
	v_mfma_f32_16x16x32_bf16 v[50:53], v[174:177], v[190:193], v[50:53]
	v_mfma_f32_16x16x32_bf16 v[42:45], v[182:185], v[190:193], v[42:45]
	v_mfma_f32_16x16x32_bf16 v[34:37], v[174:177], v[198:201], v[34:37]
	v_mfma_f32_16x16x32_bf16 v[26:29], v[182:185], v[198:201], v[26:29]
	v_mfma_f32_16x16x32_bf16 v[18:21], v[174:177], v[206:209], v[18:21]
	v_mfma_f32_16x16x32_bf16 v[10:13], v[182:185], v[206:209], v[10:13]
	v_mfma_f32_16x16x32_bf16 v[6:9], v[174:177], v[214:217], v[6:9]
	v_mfma_f32_16x16x32_bf16 v[2:5], v[182:185], v[214:217], v[2:5]
	s_setprio 0
	s_barrier
	s_add_i32 s75, 0, 0x18000
	v_add_u32_e32 v153, s75, v148
	s_add_i32 s76, 0, 0x1c000
	ds_read_b128 v[154:157], v153
	ds_read_b128 v[158:161], v153 offset:1024
	ds_read_b128 v[162:165], v153 offset:2048
	ds_read_b128 v[166:169], v153 offset:3072
	v_add_u32_e32 v153, s76, v148
	ds_read_b128 v[170:173], v153
	ds_read_b128 v[174:177], v153 offset:1024
	ds_read_b128 v[178:181], v153 offset:2048
	ds_read_b128 v[182:185], v153 offset:3072
	s_add_u32 s28, s62, 0x2b0000
	s_addc_u32 s29, s63, 0
	s_mov_b32 m0, s37
	v_lshl_add_u64 v[224:225], s[28:29], 0, v[130:131]
	ds_read_b128 v[186:189], v152 offset:32768
	ds_read_b128 v[190:193], v152 offset:33792
	ds_read_b128 v[194:197], v152 offset:34816
	ds_read_b128 v[198:201], v152 offset:35840
	ds_read_b128 v[202:205], v152 offset:36864
	ds_read_b128 v[206:209], v152 offset:37888
	ds_read_b128 v[210:213], v152 offset:38912
	ds_read_b128 v[214:217], v152 offset:39936
	global_load_lds_dwordx4 v[224:225], off
	v_lshl_add_u64 v[224:225], s[28:29], 0, v[134:135]
	s_mov_b32 m0, s42
	s_nop 0
	global_load_lds_dwordx4 v[224:225], off
	s_waitcnt vmcnt(8)
	s_waitcnt lgkmcnt(0)
	s_barrier
	s_setprio 1
	s_waitcnt lgkmcnt(0)
	v_mfma_f32_16x16x32_bf16 v[126:129], v[154:157], v[186:189], v[126:129]
	v_mfma_f32_16x16x32_bf16 v[122:125], v[162:165], v[186:189], v[122:125]
	v_mfma_f32_16x16x32_bf16 v[118:121], v[154:157], v[194:197], v[118:121]
	v_mfma_f32_16x16x32_bf16 v[110:113], v[162:165], v[194:197], v[110:113]
	v_mfma_f32_16x16x32_bf16 v[102:105], v[154:157], v[202:205], v[102:105]
	v_mfma_f32_16x16x32_bf16 v[94:97], v[162:165], v[202:205], v[94:97]
	v_mfma_f32_16x16x32_bf16 v[82:85], v[154:157], v[210:213], v[82:85]
	v_mfma_f32_16x16x32_bf16 v[74:77], v[162:165], v[210:213], v[74:77]
	v_mfma_f32_16x16x32_bf16 v[126:129], v[158:161], v[190:193], v[126:129]
	v_mfma_f32_16x16x32_bf16 v[122:125], v[166:169], v[190:193], v[122:125]
	v_mfma_f32_16x16x32_bf16 v[118:121], v[158:161], v[198:201], v[118:121]
	v_mfma_f32_16x16x32_bf16 v[110:113], v[166:169], v[198:201], v[110:113]
	v_mfma_f32_16x16x32_bf16 v[102:105], v[158:161], v[206:209], v[102:105]
	v_mfma_f32_16x16x32_bf16 v[94:97], v[166:169], v[206:209], v[94:97]
	v_mfma_f32_16x16x32_bf16 v[82:85], v[158:161], v[214:217], v[82:85]
	v_mfma_f32_16x16x32_bf16 v[74:77], v[166:169], v[214:217], v[74:77]
	s_setprio 0
	s_setprio 1
	v_mfma_f32_16x16x32_bf16 v[114:117], v[170:173], v[186:189], v[114:117]
	v_mfma_f32_16x16x32_bf16 v[106:109], v[178:181], v[186:189], v[106:109]
	v_mfma_f32_16x16x32_bf16 v[98:101], v[170:173], v[194:197], v[98:101]
	v_mfma_f32_16x16x32_bf16 v[90:93], v[178:181], v[194:197], v[90:93]
	v_mfma_f32_16x16x32_bf16 v[86:89], v[170:173], v[202:205], v[86:89]
	v_mfma_f32_16x16x32_bf16 v[78:81], v[178:181], v[202:205], v[78:81]
	v_mfma_f32_16x16x32_bf16 v[70:73], v[170:173], v[210:213], v[70:73]
	v_mfma_f32_16x16x32_bf16 v[66:69], v[178:181], v[210:213], v[66:69]
	v_mfma_f32_16x16x32_bf16 v[114:117], v[174:177], v[190:193], v[114:117]
	v_mfma_f32_16x16x32_bf16 v[106:109], v[182:185], v[190:193], v[106:109]
	v_mfma_f32_16x16x32_bf16 v[98:101], v[174:177], v[198:201], v[98:101]
	v_mfma_f32_16x16x32_bf16 v[90:93], v[182:185], v[198:201], v[90:93]
	v_mfma_f32_16x16x32_bf16 v[86:89], v[174:177], v[206:209], v[86:89]
	v_mfma_f32_16x16x32_bf16 v[78:81], v[182:185], v[206:209], v[78:81]
	v_mfma_f32_16x16x32_bf16 v[70:73], v[174:177], v[214:217], v[70:73]
	v_mfma_f32_16x16x32_bf16 v[66:69], v[182:185], v[214:217], v[66:69]
	s_setprio 0
	s_barrier
	s_add_i32 s28, s75, s3
	v_lshl_add_u64 v[146:147], v[146:147], 0, s[22:23]
	s_mov_b32 m0, s28
	ds_read_b128 v[186:189], v152 offset:49152
	ds_read_b128 v[190:193], v152 offset:50176
	ds_read_b128 v[194:197], v152 offset:51200
	ds_read_b128 v[198:201], v152 offset:52224
	ds_read_b128 v[202:205], v152 offset:53248
	ds_read_b128 v[206:209], v152 offset:54272
	ds_read_b128 v[210:213], v152 offset:55296
	ds_read_b128 v[214:217], v152 offset:56320
	global_load_lds_dwordx4 v[146:147], off
	s_add_i32 m0, s28, 0x2000
	s_add_u32 s28, s40, 0x2b0080
	v_lshl_add_u64 v[146:147], v[218:219], 0, s[22:23]
	s_addc_u32 s29, s41, 0
	s_add_i32 s40, s76, s3
	global_load_lds_dwordx4 v[146:147], off
	v_lshl_add_u64 v[146:147], s[28:29], 0, v[132:133]
	s_mov_b32 m0, s40
	s_nop 0
	global_load_lds_dwordx4 v[146:147], off
	v_lshl_add_u64 v[146:147], s[28:29], 0, v[136:137]
	s_add_i32 m0, s40, 0x2000
	s_nop 0
	global_load_lds_dwordx4 v[146:147], off
	v_lshl_add_u64 v[146:147], v[220:221], 0, s[22:23]
	s_mov_b32 m0, s44
	s_nop 0
	global_load_lds_dwordx4 v[146:147], off
	v_lshl_add_u64 v[146:147], v[222:223], 0, s[22:23]
	s_mov_b32 m0, s45
	s_nop 0
	global_load_lds_dwordx4 v[146:147], off
	s_waitcnt vmcnt(8)
	s_waitcnt lgkmcnt(0)
	s_barrier
	s_setprio 1
	s_waitcnt lgkmcnt(0)
	v_mfma_f32_16x16x32_bf16 v[62:65], v[154:157], v[186:189], v[62:65]
	v_mfma_f32_16x16x32_bf16 v[58:61], v[162:165], v[186:189], v[58:61]
	v_mfma_f32_16x16x32_bf16 v[54:57], v[154:157], v[194:197], v[54:57]
	v_mfma_f32_16x16x32_bf16 v[46:49], v[162:165], v[194:197], v[46:49]
	v_mfma_f32_16x16x32_bf16 v[38:41], v[154:157], v[202:205], v[38:41]
	v_mfma_f32_16x16x32_bf16 v[30:33], v[162:165], v[202:205], v[30:33]
	v_mfma_f32_16x16x32_bf16 v[22:25], v[154:157], v[210:213], v[22:25]
	v_mfma_f32_16x16x32_bf16 v[14:17], v[162:165], v[210:213], v[14:17]
	v_mfma_f32_16x16x32_bf16 v[62:65], v[158:161], v[190:193], v[62:65]
	v_mfma_f32_16x16x32_bf16 v[58:61], v[166:169], v[190:193], v[58:61]
	v_mfma_f32_16x16x32_bf16 v[54:57], v[158:161], v[198:201], v[54:57]
	v_mfma_f32_16x16x32_bf16 v[46:49], v[166:169], v[198:201], v[46:49]
	v_mfma_f32_16x16x32_bf16 v[38:41], v[158:161], v[206:209], v[38:41]
	v_mfma_f32_16x16x32_bf16 v[30:33], v[166:169], v[206:209], v[30:33]
	v_mfma_f32_16x16x32_bf16 v[22:25], v[158:161], v[214:217], v[22:25]
	v_mfma_f32_16x16x32_bf16 v[14:17], v[166:169], v[214:217], v[14:17]
	s_setprio 0
	s_setprio 1
	v_mfma_f32_16x16x32_bf16 v[50:53], v[170:173], v[186:189], v[50:53]
	v_mfma_f32_16x16x32_bf16 v[42:45], v[178:181], v[186:189], v[42:45]
	v_mfma_f32_16x16x32_bf16 v[34:37], v[170:173], v[194:197], v[34:37]
	v_mfma_f32_16x16x32_bf16 v[26:29], v[178:181], v[194:197], v[26:29]
	v_mfma_f32_16x16x32_bf16 v[18:21], v[170:173], v[202:205], v[18:21]
	v_mfma_f32_16x16x32_bf16 v[10:13], v[178:181], v[202:205], v[10:13]
	v_mfma_f32_16x16x32_bf16 v[6:9], v[170:173], v[210:213], v[6:9]
	v_mfma_f32_16x16x32_bf16 v[2:5], v[178:181], v[210:213], v[2:5]
	v_mfma_f32_16x16x32_bf16 v[50:53], v[174:177], v[190:193], v[50:53]
	v_mfma_f32_16x16x32_bf16 v[42:45], v[182:185], v[190:193], v[42:45]
	v_mfma_f32_16x16x32_bf16 v[34:37], v[174:177], v[198:201], v[34:37]
	v_mfma_f32_16x16x32_bf16 v[26:29], v[182:185], v[198:201], v[26:29]
	v_mfma_f32_16x16x32_bf16 v[18:21], v[174:177], v[206:209], v[18:21]
	v_mfma_f32_16x16x32_bf16 v[10:13], v[182:185], v[206:209], v[10:13]
	v_mfma_f32_16x16x32_bf16 v[6:9], v[174:177], v[214:217], v[6:9]
	v_mfma_f32_16x16x32_bf16 v[2:5], v[182:185], v[214:217], v[2:5]
	s_add_i32 s74, s74, 2
	s_add_u32 s72, s72, 0x100
	s_addc_u32 s73, s73, 0
	s_cmpk_gt_u32 s74, 0xa9
	s_mov_b64 s[28:29], s[30:31]
	s_setprio 0
	s_barrier
	s_cbranch_scc0 .LBB0_260
	s_and_b64 vcc, exec, s[24:25]
	s_cbranch_vccz .LBB0_263
	s_barrier

.LBB0_387:
	ds_read_b128 v[152:155], v148
	ds_read_b128 v[156:159], v148 offset:1024
	ds_read_b128 v[160:163], v148 offset:2048
	ds_read_b128 v[164:167], v148 offset:3072
	ds_read_b128 v[168:171], v149
	ds_read_b128 v[172:175], v149 offset:1024
	ds_read_b128 v[176:179], v149 offset:2048
	ds_read_b128 v[180:183], v149 offset:3072
	s_add_u32 s40, s30, 0xfff00080
	s_addc_u32 s41, s31, -1
	s_cmp_eq_u32 s71, 60
	s_cselect_b32 s69, s23, s41
	s_cselect_b32 s68, s63, s40
	s_cselect_b32 s41, s13, s70
	s_cselect_b32 s40, s66, s67
	v_lshl_add_u64 v[144:145], s[30:31], 0, v[134:135]
	s_add_i32 m0, s29, 0xc000
	ds_read_b128 v[184:187], v150
	ds_read_b128 v[188:191], v150 offset:1024
	ds_read_b128 v[192:195], v150 offset:2048
	ds_read_b128 v[196:199], v150 offset:3072
	ds_read_b128 v[200:203], v150 offset:4096
	ds_read_b128 v[204:207], v150 offset:5120
	ds_read_b128 v[208:211], v150 offset:6144
	ds_read_b128 v[212:215], v150 offset:7168
	global_load_lds_dwordx4 v[144:145], off
	v_lshl_add_u64 v[144:145], s[30:31], 0, v[136:137]
	s_add_i32 m0, s29, 0xe000
	s_nop 0
	global_load_lds_dwordx4 v[144:145], off
	s_waitcnt vmcnt(8)
	s_waitcnt lgkmcnt(0)
	s_barrier
	s_setprio 1
	s_waitcnt lgkmcnt(0)
	v_mfma_f32_16x16x32_bf16 v[126:129], v[152:155], v[184:187], v[126:129]
	v_mfma_f32_16x16x32_bf16 v[122:125], v[160:163], v[184:187], v[122:125]
	v_mfma_f32_16x16x32_bf16 v[114:117], v[152:155], v[192:195], v[114:117]
	v_mfma_f32_16x16x32_bf16 v[106:109], v[160:163], v[192:195], v[106:109]
	v_mfma_f32_16x16x32_bf16 v[98:101], v[152:155], v[200:203], v[98:101]
	v_mfma_f32_16x16x32_bf16 v[90:93], v[160:163], v[200:203], v[90:93]
	v_mfma_f32_16x16x32_bf16 v[82:85], v[152:155], v[208:211], v[82:85]
	v_mfma_f32_16x16x32_bf16 v[74:77], v[160:163], v[208:211], v[74:77]
	v_mfma_f32_16x16x32_bf16 v[126:129], v[156:159], v[188:191], v[126:129]
	v_mfma_f32_16x16x32_bf16 v[122:125], v[164:167], v[188:191], v[122:125]
	v_mfma_f32_16x16x32_bf16 v[114:117], v[156:159], v[196:199], v[114:117]
	v_mfma_f32_16x16x32_bf16 v[106:109], v[164:167], v[196:199], v[106:109]
	v_mfma_f32_16x16x32_bf16 v[98:101], v[156:159], v[204:207], v[98:101]
	v_mfma_f32_16x16x32_bf16 v[90:93], v[164:167], v[204:207], v[90:93]
	v_mfma_f32_16x16x32_bf16 v[82:85], v[156:159], v[212:215], v[82:85]
	v_mfma_f32_16x16x32_bf16 v[74:77], v[164:167], v[212:215], v[74:77]
	s_setprio 0
	s_setprio 1
	v_mfma_f32_16x16x32_bf16 v[118:121], v[168:171], v[184:187], v[118:121]
	v_mfma_f32_16x16x32_bf16 v[110:113], v[176:179], v[184:187], v[110:113]
	v_mfma_f32_16x16x32_bf16 v[102:105], v[168:171], v[192:195], v[102:105]
	v_mfma_f32_16x16x32_bf16 v[94:97], v[176:179], v[192:195], v[94:97]
	v_mfma_f32_16x16x32_bf16 v[86:89], v[168:171], v[200:203], v[86:89]
	v_mfma_f32_16x16x32_bf16 v[78:81], v[176:179], v[200:203], v[78:81]
	v_mfma_f32_16x16x32_bf16 v[70:73], v[168:171], v[208:211], v[70:73]
	v_mfma_f32_16x16x32_bf16 v[66:69], v[176:179], v[208:211], v[66:69]
	v_mfma_f32_16x16x32_bf16 v[118:121], v[172:175], v[188:191], v[118:121]
	v_mfma_f32_16x16x32_bf16 v[110:113], v[180:183], v[188:191], v[110:113]
	v_mfma_f32_16x16x32_bf16 v[102:105], v[172:175], v[196:199], v[102:105]
	v_mfma_f32_16x16x32_bf16 v[94:97], v[180:183], v[196:199], v[94:97]
	v_mfma_f32_16x16x32_bf16 v[86:89], v[172:175], v[204:207], v[86:89]
	v_mfma_f32_16x16x32_bf16 v[78:81], v[180:183], v[204:207], v[78:81]
	v_mfma_f32_16x16x32_bf16 v[70:73], v[172:175], v[212:215], v[70:73]
	v_mfma_f32_16x16x32_bf16 v[66:69], v[180:183], v[212:215], v[66:69]
	s_setprio 0
	s_barrier
	s_add_i32 s72, s50, s36
	v_lshl_add_u64 v[144:145], s[40:41], 0, v[132:133]
	s_mov_b32 m0, s72
	ds_read_b128 v[184:187], v150 offset:16384
	ds_read_b128 v[188:191], v150 offset:17408
	ds_read_b128 v[192:195], v150 offset:18432
	ds_read_b128 v[196:199], v150 offset:19456
	ds_read_b128 v[200:203], v150 offset:20480
	ds_read_b128 v[204:207], v150 offset:21504
	ds_read_b128 v[208:211], v150 offset:22528
	ds_read_b128 v[212:215], v150 offset:23552
	global_load_lds_dwordx4 v[144:145], off
	s_add_i32 m0, s72, 0x2000
	s_add_u32 s72, s40, 0x100000
	v_lshl_add_u64 v[216:217], s[40:41], 0, v[130:131]
	s_addc_u32 s73, s41, 0
	s_add_i32 s74, s51, s36
	global_load_lds_dwordx4 v[216:217], off
	v_lshl_add_u64 v[218:219], s[72:73], 0, v[132:133]
	s_mov_b32 m0, s74
	v_lshl_add_u64 v[220:221], s[68:69], 0, v[130:131]
	global_load_lds_dwordx4 v[218:219], off
	v_lshl_add_u64 v[218:219], s[72:73], 0, v[130:131]
	s_add_i32 m0, s74, 0x2000
	s_nop 0
	global_load_lds_dwordx4 v[218:219], off
	v_lshl_add_u64 v[218:219], s[68:69], 0, v[132:133]
	s_mov_b32 m0, s29
	s_nop 0
	global_load_lds_dwordx4 v[218:219], off
	s_mov_b32 m0, s43
	s_nop 0
	global_load_lds_dwordx4 v[220:221], off
	s_waitcnt vmcnt(8)
	s_waitcnt lgkmcnt(0)
	s_barrier
	s_setprio 1
	s_waitcnt lgkmcnt(0)
	v_mfma_f32_16x16x32_bf16 v[62:65], v[152:155], v[184:187], v[62:65]
	v_mfma_f32_16x16x32_bf16 v[58:61], v[160:163], v[184:187], v[58:61]
	v_mfma_f32_16x16x32_bf16 v[50:53], v[152:155], v[192:195], v[50:53]
	v_mfma_f32_16x16x32_bf16 v[42:45], v[160:163], v[192:195], v[42:45]
	v_mfma_f32_16x16x32_bf16 v[34:37], v[152:155], v[200:203], v[34:37]
	v_mfma_f32_16x16x32_bf16 v[26:29], v[160:163], v[200:203], v[26:29]
	v_mfma_f32_16x16x32_bf16 v[18:21], v[152:155], v[208:211], v[18:21]
	v_mfma_f32_16x16x32_bf16 v[10:13], v[160:163], v[208:211], v[10:13]
	v_mfma_f32_16x16x32_bf16 v[62:65], v[156:159], v[188:191], v[62:65]
	v_mfma_f32_16x16x32_bf16 v[58:61], v[164:167], v[188:191], v[58:61]
	v_mfma_f32_16x16x32_bf16 v[50:53], v[156:159], v[196:199], v[50:53]
	v_mfma_f32_16x16x32_bf16 v[42:45], v[164:167], v[196:199], v[42:45]
	v_mfma_f32_16x16x32_bf16 v[34:37], v[156:159], v[204:207], v[34:37]
	v_mfma_f32_16x16x32_bf16 v[26:29], v[164:167], v[204:207], v[26:29]
	v_mfma_f32_16x16x32_bf16 v[18:21], v[156:159], v[212:215], v[18:21]
	v_mfma_f32_16x16x32_bf16 v[10:13], v[164:167], v[212:215], v[10:13]
	s_setprio 0
	s_setprio 1
	v_mfma_f32_16x16x32_bf16 v[54:57], v[168:171], v[184:187], v[54:57]
	v_mfma_f32_16x16x32_bf16 v[46:49], v[176:179], v[184:187], v[46:49]
	v_mfma_f32_16x16x32_bf16 v[38:41], v[168:171], v[192:195], v[38:41]
	v_mfma_f32_16x16x32_bf16 v[30:33], v[176:179], v[192:195], v[30:33]
	v_mfma_f32_16x16x32_bf16 v[22:25], v[168:171], v[200:203], v[22:25]
	v_mfma_f32_16x16x32_bf16 v[14:17], v[176:179], v[200:203], v[14:17]
	v_mfma_f32_16x16x32_bf16 v[6:9], v[168:171], v[208:211], v[6:9]
	v_mfma_f32_16x16x32_bf16 v[2:5], v[176:179], v[208:211], v[2:5]
	v_mfma_f32_16x16x32_bf16 v[54:57], v[172:175], v[188:191], v[54:57]
	v_mfma_f32_16x16x32_bf16 v[46:49], v[180:183], v[188:191], v[46:49]
	v_mfma_f32_16x16x32_bf16 v[38:41], v[172:175], v[196:199], v[38:41]
	v_mfma_f32_16x16x32_bf16 v[30:33], v[180:183], v[196:199], v[30:33]
	v_mfma_f32_16x16x32_bf16 v[22:25], v[172:175], v[204:207], v[22:25]
	v_mfma_f32_16x16x32_bf16 v[14:17], v[180:183], v[204:207], v[14:17]
	v_mfma_f32_16x16x32_bf16 v[6:9], v[172:175], v[212:215], v[6:9]
	v_mfma_f32_16x16x32_bf16 v[2:5], v[180:183], v[212:215], v[2:5]
	s_setprio 0
	s_barrier
	s_add_i32 s72, 0, 0x18000
	v_add_u32_e32 v142, s72, v146
	s_add_i32 s73, 0, 0x1c000
	ds_read_b128 v[152:155], v142
	ds_read_b128 v[156:159], v142 offset:1024
	ds_read_b128 v[160:163], v142 offset:2048
	ds_read_b128 v[164:167], v142 offset:3072
	v_add_u32_e32 v142, s73, v146
	ds_read_b128 v[168:171], v142
	ds_read_b128 v[172:175], v142 offset:1024
	ds_read_b128 v[176:179], v142 offset:2048
	ds_read_b128 v[180:183], v142 offset:3072
	s_add_u32 s68, s68, 0x100000
	s_addc_u32 s69, s69, 0
	s_mov_b32 m0, s44
	v_lshl_add_u64 v[222:223], s[68:69], 0, v[132:133]
	ds_read_b128 v[184:187], v150 offset:32768
	ds_read_b128 v[188:191], v150 offset:33792
	ds_read_b128 v[192:195], v150 offset:34816
	ds_read_b128 v[196:199], v150 offset:35840
	ds_read_b128 v[200:203], v150 offset:36864
	ds_read_b128 v[204:207], v150 offset:37888
	ds_read_b128 v[208:211], v150 offset:38912
	ds_read_b128 v[212:215], v150 offset:39936
	global_load_lds_dwordx4 v[222:223], off
	v_lshl_add_u64 v[222:223], s[68:69], 0, v[130:131]
	s_mov_b32 m0, s45
	s_nop 0
	global_load_lds_dwordx4 v[222:223], off
	s_waitcnt vmcnt(8)
	s_waitcnt lgkmcnt(0)
	s_barrier
	s_setprio 1
	s_waitcnt lgkmcnt(0)
	v_mfma_f32_16x16x32_bf16 v[126:129], v[152:155], v[184:187], v[126:129]
	v_mfma_f32_16x16x32_bf16 v[122:125], v[160:163], v[184:187], v[122:125]
	v_mfma_f32_16x16x32_bf16 v[114:117], v[152:155], v[192:195], v[114:117]
	v_mfma_f32_16x16x32_bf16 v[106:109], v[160:163], v[192:195], v[106:109]
	v_mfma_f32_16x16x32_bf16 v[98:101], v[152:155], v[200:203], v[98:101]
	v_mfma_f32_16x16x32_bf16 v[90:93], v[160:163], v[200:203], v[90:93]
	v_mfma_f32_16x16x32_bf16 v[82:85], v[152:155], v[208:211], v[82:85]
	v_mfma_f32_16x16x32_bf16 v[74:77], v[160:163], v[208:211], v[74:77]
	v_mfma_f32_16x16x32_bf16 v[126:129], v[156:159], v[188:191], v[126:129]
	v_mfma_f32_16x16x32_bf16 v[122:125], v[164:167], v[188:191], v[122:125]
	v_mfma_f32_16x16x32_bf16 v[114:117], v[156:159], v[196:199], v[114:117]
	v_mfma_f32_16x16x32_bf16 v[106:109], v[164:167], v[196:199], v[106:109]
	v_mfma_f32_16x16x32_bf16 v[98:101], v[156:159], v[204:207], v[98:101]
	v_mfma_f32_16x16x32_bf16 v[90:93], v[164:167], v[204:207], v[90:93]
	v_mfma_f32_16x16x32_bf16 v[82:85], v[156:159], v[212:215], v[82:85]
	v_mfma_f32_16x16x32_bf16 v[74:77], v[164:167], v[212:215], v[74:77]
	s_setprio 0
	s_setprio 1
	v_mfma_f32_16x16x32_bf16 v[118:121], v[168:171], v[184:187], v[118:121]
	v_mfma_f32_16x16x32_bf16 v[110:113], v[176:179], v[184:187], v[110:113]
	v_mfma_f32_16x16x32_bf16 v[102:105], v[168:171], v[192:195], v[102:105]
	v_mfma_f32_16x16x32_bf16 v[94:97], v[176:179], v[192:195], v[94:97]
	v_mfma_f32_16x16x32_bf16 v[86:89], v[168:171], v[200:203], v[86:89]
	v_mfma_f32_16x16x32_bf16 v[78:81], v[176:179], v[200:203], v[78:81]
	v_mfma_f32_16x16x32_bf16 v[70:73], v[168:171], v[208:211], v[70:73]
	v_mfma_f32_16x16x32_bf16 v[66:69], v[176:179], v[208:211], v[66:69]
	v_mfma_f32_16x16x32_bf16 v[118:121], v[172:175], v[188:191], v[118:121]
	v_mfma_f32_16x16x32_bf16 v[110:113], v[180:183], v[188:191], v[110:113]
	v_mfma_f32_16x16x32_bf16 v[102:105], v[172:175], v[196:199], v[102:105]
	v_mfma_f32_16x16x32_bf16 v[94:97], v[180:183], v[196:199], v[94:97]
	v_mfma_f32_16x16x32_bf16 v[86:89], v[172:175], v[204:207], v[86:89]
	v_mfma_f32_16x16x32_bf16 v[78:81], v[180:183], v[204:207], v[78:81]
	v_mfma_f32_16x16x32_bf16 v[70:73], v[172:175], v[212:215], v[70:73]
	v_mfma_f32_16x16x32_bf16 v[66:69], v[180:183], v[212:215], v[66:69]
	s_setprio 0
	s_barrier
	s_add_i32 s68, s72, s36
	v_lshl_add_u64 v[144:145], v[144:145], 0, s[8:9]
	s_mov_b32 m0, s68
	ds_read_b128 v[184:187], v150 offset:49152
	ds_read_b128 v[188:191], v150 offset:50176
	ds_read_b128 v[192:195], v150 offset:51200
	ds_read_b128 v[196:199], v150 offset:52224
	ds_read_b128 v[200:203], v150 offset:53248
	ds_read_b128 v[204:207], v150 offset:54272
	ds_read_b128 v[208:211], v150 offset:55296
	ds_read_b128 v[212:215], v150 offset:56320
	global_load_lds_dwordx4 v[144:145], off
	s_add_i32 m0, s68, 0x2000
	s_add_u32 s40, s40, 0x100080
	v_lshl_add_u64 v[144:145], v[216:217], 0, s[8:9]
	s_addc_u32 s41, s41, 0
	s_add_i32 s68, s73, s36
	global_load_lds_dwordx4 v[144:145], off
	v_lshl_add_u64 v[144:145], s[40:41], 0, v[132:133]
	s_mov_b32 m0, s68
	s_nop 0
	global_load_lds_dwordx4 v[144:145], off
	v_lshl_add_u64 v[144:145], s[40:41], 0, v[130:131]
	s_add_i32 m0, s68, 0x2000
	s_nop 0
	global_load_lds_dwordx4 v[144:145], off
	v_lshl_add_u64 v[144:145], v[218:219], 0, s[8:9]
	s_mov_b32 m0, s47
	s_nop 0
	global_load_lds_dwordx4 v[144:145], off
	v_lshl_add_u64 v[144:145], v[220:221], 0, s[8:9]
	s_mov_b32 m0, s48
	s_nop 0
	global_load_lds_dwordx4 v[144:145], off
	s_waitcnt vmcnt(8)
	s_waitcnt lgkmcnt(0)
	s_barrier
	s_setprio 1
	s_waitcnt lgkmcnt(0)
	v_mfma_f32_16x16x32_bf16 v[62:65], v[152:155], v[184:187], v[62:65]
	v_mfma_f32_16x16x32_bf16 v[58:61], v[160:163], v[184:187], v[58:61]
	v_mfma_f32_16x16x32_bf16 v[50:53], v[152:155], v[192:195], v[50:53]
	v_mfma_f32_16x16x32_bf16 v[42:45], v[160:163], v[192:195], v[42:45]
	v_mfma_f32_16x16x32_bf16 v[34:37], v[152:155], v[200:203], v[34:37]
	v_mfma_f32_16x16x32_bf16 v[26:29], v[160:163], v[200:203], v[26:29]
	v_mfma_f32_16x16x32_bf16 v[18:21], v[152:155], v[208:211], v[18:21]
	v_mfma_f32_16x16x32_bf16 v[10:13], v[160:163], v[208:211], v[10:13]
	v_mfma_f32_16x16x32_bf16 v[62:65], v[156:159], v[188:191], v[62:65]
	v_mfma_f32_16x16x32_bf16 v[58:61], v[164:167], v[188:191], v[58:61]
	v_mfma_f32_16x16x32_bf16 v[50:53], v[156:159], v[196:199], v[50:53]
	v_mfma_f32_16x16x32_bf16 v[42:45], v[164:167], v[196:199], v[42:45]
	v_mfma_f32_16x16x32_bf16 v[34:37], v[156:159], v[204:207], v[34:37]
	v_mfma_f32_16x16x32_bf16 v[26:29], v[164:167], v[204:207], v[26:29]
	v_mfma_f32_16x16x32_bf16 v[18:21], v[156:159], v[212:215], v[18:21]
	v_mfma_f32_16x16x32_bf16 v[10:13], v[164:167], v[212:215], v[10:13]
	s_setprio 0
	s_setprio 1
	v_mfma_f32_16x16x32_bf16 v[54:57], v[168:171], v[184:187], v[54:57]
	v_mfma_f32_16x16x32_bf16 v[46:49], v[176:179], v[184:187], v[46:49]
	v_mfma_f32_16x16x32_bf16 v[38:41], v[168:171], v[192:195], v[38:41]
	v_mfma_f32_16x16x32_bf16 v[30:33], v[176:179], v[192:195], v[30:33]
	v_mfma_f32_16x16x32_bf16 v[22:25], v[168:171], v[200:203], v[22:25]
	v_mfma_f32_16x16x32_bf16 v[14:17], v[176:179], v[200:203], v[14:17]
	v_mfma_f32_16x16x32_bf16 v[6:9], v[168:171], v[208:211], v[6:9]
	v_mfma_f32_16x16x32_bf16 v[2:5], v[176:179], v[208:211], v[2:5]
	v_mfma_f32_16x16x32_bf16 v[54:57], v[172:175], v[188:191], v[54:57]
	v_mfma_f32_16x16x32_bf16 v[46:49], v[180:183], v[188:191], v[46:49]
	v_mfma_f32_16x16x32_bf16 v[38:41], v[172:175], v[196:199], v[38:41]
	v_mfma_f32_16x16x32_bf16 v[30:33], v[180:183], v[196:199], v[30:33]
	v_mfma_f32_16x16x32_bf16 v[22:25], v[172:175], v[204:207], v[22:25]
	v_mfma_f32_16x16x32_bf16 v[14:17], v[180:183], v[204:207], v[14:17]
	v_mfma_f32_16x16x32_bf16 v[6:9], v[172:175], v[212:215], v[6:9]
	v_mfma_f32_16x16x32_bf16 v[2:5], v[180:183], v[212:215], v[2:5]
	s_add_i32 s71, s71, 2
	s_add_u32 s30, s30, 0x100
	s_addc_u32 s31, s31, 0
	s_add_u32 s67, s67, 0x100
	s_addc_u32 s70, s70, 0
	s_cmp_gt_u32 s71, 61
	s_setprio 0
	s_barrier
	s_cbranch_scc0 .LBB0_387
	s_and_b64 vcc, exec, s[10:11]
	s_cbranch_vccz .LBB0_390
	s_barrier

.LBB0_1211:
	ds_read_b128 v[154:157], v150
	ds_read_b128 v[158:161], v150 offset:1024
	ds_read_b128 v[162:165], v150 offset:2048
	ds_read_b128 v[166:169], v150 offset:3072
	ds_read_b128 v[170:173], v151
	ds_read_b128 v[174:177], v151 offset:1024
	ds_read_b128 v[178:181], v151 offset:2048
	ds_read_b128 v[182:185], v151 offset:3072
	s_add_u32 s40, s36, 0xfff00080
	s_addc_u32 s41, s37, -1
	s_cmp_eq_u32 s64, 60
	s_cselect_b32 s43, s25, s41
	s_cselect_b32 s42, s60, s40
	s_cselect_b32 s41, s23, s63
	s_cselect_b32 s40, s61, s62
	v_lshl_add_u64 v[146:147], s[36:37], 0, v[138:139]
	s_add_i32 m0, s31, 0xc000
	ds_read_b128 v[186:189], v152
	ds_read_b128 v[190:193], v152 offset:1024
	ds_read_b128 v[194:197], v152 offset:2048
	ds_read_b128 v[198:201], v152 offset:3072
	ds_read_b128 v[202:205], v152 offset:4096
	ds_read_b128 v[206:209], v152 offset:5120
	ds_read_b128 v[210:213], v152 offset:6144
	ds_read_b128 v[214:217], v152 offset:7168
	global_load_lds_dwordx4 v[146:147], off
	v_lshl_add_u64 v[146:147], s[36:37], 0, v[140:141]
	s_add_i32 m0, s31, 0xe000
	s_nop 0
	global_load_lds_dwordx4 v[146:147], off
	s_waitcnt vmcnt(8)
	s_waitcnt lgkmcnt(0)
	s_barrier
	s_setprio 1
	s_waitcnt lgkmcnt(0)
	v_mfma_f32_16x16x32_bf16 v[126:129], v[154:157], v[186:189], v[126:129]
	v_mfma_f32_16x16x32_bf16 v[122:125], v[162:165], v[186:189], v[122:125]
	v_mfma_f32_16x16x32_bf16 v[118:121], v[154:157], v[194:197], v[118:121]
	v_mfma_f32_16x16x32_bf16 v[110:113], v[162:165], v[194:197], v[110:113]
	v_mfma_f32_16x16x32_bf16 v[102:105], v[154:157], v[202:205], v[102:105]
	v_mfma_f32_16x16x32_bf16 v[94:97], v[162:165], v[202:205], v[94:97]
	v_mfma_f32_16x16x32_bf16 v[86:89], v[154:157], v[210:213], v[86:89]
	v_mfma_f32_16x16x32_bf16 v[78:81], v[162:165], v[210:213], v[78:81]
	v_mfma_f32_16x16x32_bf16 v[126:129], v[158:161], v[190:193], v[126:129]
	v_mfma_f32_16x16x32_bf16 v[122:125], v[166:169], v[190:193], v[122:125]
	v_mfma_f32_16x16x32_bf16 v[118:121], v[158:161], v[198:201], v[118:121]
	v_mfma_f32_16x16x32_bf16 v[110:113], v[166:169], v[198:201], v[110:113]
	v_mfma_f32_16x16x32_bf16 v[102:105], v[158:161], v[206:209], v[102:105]
	v_mfma_f32_16x16x32_bf16 v[94:97], v[166:169], v[206:209], v[94:97]
	v_mfma_f32_16x16x32_bf16 v[86:89], v[158:161], v[214:217], v[86:89]
	v_mfma_f32_16x16x32_bf16 v[78:81], v[166:169], v[214:217], v[78:81]
	s_setprio 0
	s_setprio 1
	v_mfma_f32_16x16x32_bf16 v[114:117], v[170:173], v[186:189], v[114:117]
	v_mfma_f32_16x16x32_bf16 v[106:109], v[178:181], v[186:189], v[106:109]
	v_mfma_f32_16x16x32_bf16 v[98:101], v[170:173], v[194:197], v[98:101]
	v_mfma_f32_16x16x32_bf16 v[90:93], v[178:181], v[194:197], v[90:93]
	v_mfma_f32_16x16x32_bf16 v[82:85], v[170:173], v[202:205], v[82:85]
	v_mfma_f32_16x16x32_bf16 v[74:77], v[178:181], v[202:205], v[74:77]
	v_mfma_f32_16x16x32_bf16 v[70:73], v[170:173], v[210:213], v[70:73]
	v_mfma_f32_16x16x32_bf16 v[66:69], v[178:181], v[210:213], v[66:69]
	v_mfma_f32_16x16x32_bf16 v[114:117], v[174:177], v[190:193], v[114:117]
	v_mfma_f32_16x16x32_bf16 v[106:109], v[182:185], v[190:193], v[106:109]
	v_mfma_f32_16x16x32_bf16 v[98:101], v[174:177], v[198:201], v[98:101]
	v_mfma_f32_16x16x32_bf16 v[90:93], v[182:185], v[198:201], v[90:93]
	v_mfma_f32_16x16x32_bf16 v[82:85], v[174:177], v[206:209], v[82:85]
	v_mfma_f32_16x16x32_bf16 v[74:77], v[182:185], v[206:209], v[74:77]
	v_mfma_f32_16x16x32_bf16 v[70:73], v[174:177], v[214:217], v[70:73]
	v_mfma_f32_16x16x32_bf16 v[66:69], v[182:185], v[214:217], v[66:69]
	s_setprio 0
	s_barrier
	s_add_i32 s65, s51, s15
	v_lshl_add_u64 v[146:147], s[40:41], 0, v[132:133]
	s_mov_b32 m0, s65
	ds_read_b128 v[186:189], v152 offset:16384
	ds_read_b128 v[190:193], v152 offset:17408
	ds_read_b128 v[194:197], v152 offset:18432
	ds_read_b128 v[198:201], v152 offset:19456
	ds_read_b128 v[202:205], v152 offset:20480
	ds_read_b128 v[206:209], v152 offset:21504
	ds_read_b128 v[210:213], v152 offset:22528
	ds_read_b128 v[214:217], v152 offset:23552
	global_load_lds_dwordx4 v[146:147], off
	s_add_i32 m0, s65, 0x2000
	s_add_u32 s66, s40, 0x100000
	v_lshl_add_u64 v[218:219], s[40:41], 0, v[136:137]
	s_addc_u32 s67, s41, 0
	s_add_i32 s65, s52, s15
	global_load_lds_dwordx4 v[218:219], off
	v_lshl_add_u64 v[220:221], s[66:67], 0, v[132:133]
	s_mov_b32 m0, s65
	v_lshl_add_u64 v[222:223], s[42:43], 0, v[134:135]
	global_load_lds_dwordx4 v[220:221], off
	v_lshl_add_u64 v[220:221], s[66:67], 0, v[136:137]
	s_add_i32 m0, s65, 0x2000
	s_nop 0
	global_load_lds_dwordx4 v[220:221], off
	v_lshl_add_u64 v[220:221], s[42:43], 0, v[130:131]
	s_mov_b32 m0, s31
	s_nop 0
	global_load_lds_dwordx4 v[220:221], off
	s_mov_b32 m0, s44
	s_nop 0
	global_load_lds_dwordx4 v[222:223], off
	s_waitcnt vmcnt(8)
	s_waitcnt lgkmcnt(0)
	s_barrier
	s_setprio 1
	s_waitcnt lgkmcnt(0)
	v_mfma_f32_16x16x32_bf16 v[62:65], v[154:157], v[186:189], v[62:65]
	v_mfma_f32_16x16x32_bf16 v[58:61], v[162:165], v[186:189], v[58:61]
	v_mfma_f32_16x16x32_bf16 v[54:57], v[154:157], v[194:197], v[54:57]
	v_mfma_f32_16x16x32_bf16 v[46:49], v[162:165], v[194:197], v[46:49]
	v_mfma_f32_16x16x32_bf16 v[38:41], v[154:157], v[202:205], v[38:41]
	v_mfma_f32_16x16x32_bf16 v[30:33], v[162:165], v[202:205], v[30:33]
	v_mfma_f32_16x16x32_bf16 v[22:25], v[154:157], v[210:213], v[22:25]
	v_mfma_f32_16x16x32_bf16 v[14:17], v[162:165], v[210:213], v[14:17]
	v_mfma_f32_16x16x32_bf16 v[62:65], v[158:161], v[190:193], v[62:65]
	v_mfma_f32_16x16x32_bf16 v[58:61], v[166:169], v[190:193], v[58:61]
	v_mfma_f32_16x16x32_bf16 v[54:57], v[158:161], v[198:201], v[54:57]
	v_mfma_f32_16x16x32_bf16 v[46:49], v[166:169], v[198:201], v[46:49]
	v_mfma_f32_16x16x32_bf16 v[38:41], v[158:161], v[206:209], v[38:41]
	v_mfma_f32_16x16x32_bf16 v[30:33], v[166:169], v[206:209], v[30:33]
	v_mfma_f32_16x16x32_bf16 v[22:25], v[158:161], v[214:217], v[22:25]
	v_mfma_f32_16x16x32_bf16 v[14:17], v[166:169], v[214:217], v[14:17]
	s_setprio 0
	s_setprio 1
	v_mfma_f32_16x16x32_bf16 v[50:53], v[170:173], v[186:189], v[50:53]
	v_mfma_f32_16x16x32_bf16 v[42:45], v[178:181], v[186:189], v[42:45]
	v_mfma_f32_16x16x32_bf16 v[34:37], v[170:173], v[194:197], v[34:37]
	v_mfma_f32_16x16x32_bf16 v[26:29], v[178:181], v[194:197], v[26:29]
	v_mfma_f32_16x16x32_bf16 v[18:21], v[170:173], v[202:205], v[18:21]
	v_mfma_f32_16x16x32_bf16 v[10:13], v[178:181], v[202:205], v[10:13]
	v_mfma_f32_16x16x32_bf16 v[6:9], v[170:173], v[210:213], v[6:9]
	v_mfma_f32_16x16x32_bf16 v[2:5], v[178:181], v[210:213], v[2:5]
	v_mfma_f32_16x16x32_bf16 v[50:53], v[174:177], v[190:193], v[50:53]
	v_mfma_f32_16x16x32_bf16 v[42:45], v[182:185], v[190:193], v[42:45]
	v_mfma_f32_16x16x32_bf16 v[34:37], v[174:177], v[198:201], v[34:37]
	v_mfma_f32_16x16x32_bf16 v[26:29], v[182:185], v[198:201], v[26:29]
	v_mfma_f32_16x16x32_bf16 v[18:21], v[174:177], v[206:209], v[18:21]
	v_mfma_f32_16x16x32_bf16 v[10:13], v[182:185], v[206:209], v[10:13]
	v_mfma_f32_16x16x32_bf16 v[6:9], v[174:177], v[214:217], v[6:9]
	v_mfma_f32_16x16x32_bf16 v[2:5], v[182:185], v[214:217], v[2:5]
	s_setprio 0
	s_barrier
	s_add_i32 s65, 0, 0x18000
	v_add_u32_e32 v153, s65, v148
	s_add_i32 s66, 0, 0x1c000
	ds_read_b128 v[154:157], v153
	ds_read_b128 v[158:161], v153 offset:1024
	ds_read_b128 v[162:165], v153 offset:2048
	ds_read_b128 v[166:169], v153 offset:3072
	v_add_u32_e32 v153, s66, v148
	ds_read_b128 v[170:173], v153
	ds_read_b128 v[174:177], v153 offset:1024
	ds_read_b128 v[178:181], v153 offset:2048
	ds_read_b128 v[182:185], v153 offset:3072
	s_add_u32 s42, s42, 0x100000
	s_addc_u32 s43, s43, 0
	s_mov_b32 m0, s45
	v_lshl_add_u64 v[224:225], s[42:43], 0, v[130:131]
	ds_read_b128 v[186:189], v152 offset:32768
	ds_read_b128 v[190:193], v152 offset:33792
	ds_read_b128 v[194:197], v152 offset:34816
	ds_read_b128 v[198:201], v152 offset:35840
	ds_read_b128 v[202:205], v152 offset:36864
	ds_read_b128 v[206:209], v152 offset:37888
	ds_read_b128 v[210:213], v152 offset:38912
	ds_read_b128 v[214:217], v152 offset:39936
	global_load_lds_dwordx4 v[224:225], off
	v_lshl_add_u64 v[224:225], s[42:43], 0, v[134:135]
	s_mov_b32 m0, s46
	s_nop 0
	global_load_lds_dwordx4 v[224:225], off
	s_waitcnt vmcnt(8)
	s_waitcnt lgkmcnt(0)
	s_barrier
	s_setprio 1
	s_waitcnt lgkmcnt(0)
	v_mfma_f32_16x16x32_bf16 v[126:129], v[154:157], v[186:189], v[126:129]
	v_mfma_f32_16x16x32_bf16 v[122:125], v[162:165], v[186:189], v[122:125]
	v_mfma_f32_16x16x32_bf16 v[118:121], v[154:157], v[194:197], v[118:121]
	v_mfma_f32_16x16x32_bf16 v[110:113], v[162:165], v[194:197], v[110:113]
	v_mfma_f32_16x16x32_bf16 v[102:105], v[154:157], v[202:205], v[102:105]
	v_mfma_f32_16x16x32_bf16 v[94:97], v[162:165], v[202:205], v[94:97]
	v_mfma_f32_16x16x32_bf16 v[86:89], v[154:157], v[210:213], v[86:89]
	v_mfma_f32_16x16x32_bf16 v[78:81], v[162:165], v[210:213], v[78:81]
	v_mfma_f32_16x16x32_bf16 v[126:129], v[158:161], v[190:193], v[126:129]
	v_mfma_f32_16x16x32_bf16 v[122:125], v[166:169], v[190:193], v[122:125]
	v_mfma_f32_16x16x32_bf16 v[118:121], v[158:161], v[198:201], v[118:121]
	v_mfma_f32_16x16x32_bf16 v[110:113], v[166:169], v[198:201], v[110:113]
	v_mfma_f32_16x16x32_bf16 v[102:105], v[158:161], v[206:209], v[102:105]
	v_mfma_f32_16x16x32_bf16 v[94:97], v[166:169], v[206:209], v[94:97]
	v_mfma_f32_16x16x32_bf16 v[86:89], v[158:161], v[214:217], v[86:89]
	v_mfma_f32_16x16x32_bf16 v[78:81], v[166:169], v[214:217], v[78:81]
	s_setprio 0
	s_setprio 1
	v_mfma_f32_16x16x32_bf16 v[114:117], v[170:173], v[186:189], v[114:117]
	v_mfma_f32_16x16x32_bf16 v[106:109], v[178:181], v[186:189], v[106:109]
	v_mfma_f32_16x16x32_bf16 v[98:101], v[170:173], v[194:197], v[98:101]
	v_mfma_f32_16x16x32_bf16 v[90:93], v[178:181], v[194:197], v[90:93]
	v_mfma_f32_16x16x32_bf16 v[82:85], v[170:173], v[202:205], v[82:85]
	v_mfma_f32_16x16x32_bf16 v[74:77], v[178:181], v[202:205], v[74:77]
	v_mfma_f32_16x16x32_bf16 v[70:73], v[170:173], v[210:213], v[70:73]
	v_mfma_f32_16x16x32_bf16 v[66:69], v[178:181], v[210:213], v[66:69]
	v_mfma_f32_16x16x32_bf16 v[114:117], v[174:177], v[190:193], v[114:117]
	v_mfma_f32_16x16x32_bf16 v[106:109], v[182:185], v[190:193], v[106:109]
	v_mfma_f32_16x16x32_bf16 v[98:101], v[174:177], v[198:201], v[98:101]
	v_mfma_f32_16x16x32_bf16 v[90:93], v[182:185], v[198:201], v[90:93]
	v_mfma_f32_16x16x32_bf16 v[82:85], v[174:177], v[206:209], v[82:85]
	v_mfma_f32_16x16x32_bf16 v[74:77], v[182:185], v[206:209], v[74:77]
	v_mfma_f32_16x16x32_bf16 v[70:73], v[174:177], v[214:217], v[70:73]
	v_mfma_f32_16x16x32_bf16 v[66:69], v[182:185], v[214:217], v[66:69]
	s_setprio 0
	s_barrier
	s_add_i32 s42, s65, s15
	v_lshl_add_u64 v[146:147], v[146:147], 0, s[10:11]
	s_mov_b32 m0, s42
	ds_read_b128 v[186:189], v152 offset:49152
	ds_read_b128 v[190:193], v152 offset:50176
	ds_read_b128 v[194:197], v152 offset:51200
	ds_read_b128 v[198:201], v152 offset:52224
	ds_read_b128 v[202:205], v152 offset:53248
	ds_read_b128 v[206:209], v152 offset:54272
	ds_read_b128 v[210:213], v152 offset:55296
	ds_read_b128 v[214:217], v152 offset:56320
	global_load_lds_dwordx4 v[146:147], off
	s_add_i32 m0, s42, 0x2000
	s_add_u32 s40, s40, 0x100080
	v_lshl_add_u64 v[146:147], v[218:219], 0, s[10:11]
	s_addc_u32 s41, s41, 0
	s_add_i32 s42, s66, s15
	global_load_lds_dwordx4 v[146:147], off
	v_lshl_add_u64 v[146:147], s[40:41], 0, v[132:133]
	s_mov_b32 m0, s42
	s_nop 0
	global_load_lds_dwordx4 v[146:147], off
	v_lshl_add_u64 v[146:147], s[40:41], 0, v[136:137]
	s_add_i32 m0, s42, 0x2000
	s_nop 0
	global_load_lds_dwordx4 v[146:147], off
	v_lshl_add_u64 v[146:147], v[220:221], 0, s[10:11]
	s_mov_b32 m0, s48
	s_nop 0
	global_load_lds_dwordx4 v[146:147], off
	v_lshl_add_u64 v[146:147], v[222:223], 0, s[10:11]
	s_mov_b32 m0, s49
	s_nop 0
	global_load_lds_dwordx4 v[146:147], off
	s_waitcnt vmcnt(8)
	s_waitcnt lgkmcnt(0)
	s_barrier
	s_setprio 1
	s_waitcnt lgkmcnt(0)
	v_mfma_f32_16x16x32_bf16 v[62:65], v[154:157], v[186:189], v[62:65]
	v_mfma_f32_16x16x32_bf16 v[58:61], v[162:165], v[186:189], v[58:61]
	v_mfma_f32_16x16x32_bf16 v[54:57], v[154:157], v[194:197], v[54:57]
	v_mfma_f32_16x16x32_bf16 v[46:49], v[162:165], v[194:197], v[46:49]
	v_mfma_f32_16x16x32_bf16 v[38:41], v[154:157], v[202:205], v[38:41]
	v_mfma_f32_16x16x32_bf16 v[30:33], v[162:165], v[202:205], v[30:33]
	v_mfma_f32_16x16x32_bf16 v[22:25], v[154:157], v[210:213], v[22:25]
	v_mfma_f32_16x16x32_bf16 v[14:17], v[162:165], v[210:213], v[14:17]
	v_mfma_f32_16x16x32_bf16 v[62:65], v[158:161], v[190:193], v[62:65]
	v_mfma_f32_16x16x32_bf16 v[58:61], v[166:169], v[190:193], v[58:61]
	v_mfma_f32_16x16x32_bf16 v[54:57], v[158:161], v[198:201], v[54:57]
	v_mfma_f32_16x16x32_bf16 v[46:49], v[166:169], v[198:201], v[46:49]
	v_mfma_f32_16x16x32_bf16 v[38:41], v[158:161], v[206:209], v[38:41]
	v_mfma_f32_16x16x32_bf16 v[30:33], v[166:169], v[206:209], v[30:33]
	v_mfma_f32_16x16x32_bf16 v[22:25], v[158:161], v[214:217], v[22:25]
	v_mfma_f32_16x16x32_bf16 v[14:17], v[166:169], v[214:217], v[14:17]
	s_setprio 0
	s_setprio 1
	v_mfma_f32_16x16x32_bf16 v[50:53], v[170:173], v[186:189], v[50:53]
	v_mfma_f32_16x16x32_bf16 v[42:45], v[178:181], v[186:189], v[42:45]
	v_mfma_f32_16x16x32_bf16 v[34:37], v[170:173], v[194:197], v[34:37]
	v_mfma_f32_16x16x32_bf16 v[26:29], v[178:181], v[194:197], v[26:29]
	v_mfma_f32_16x16x32_bf16 v[18:21], v[170:173], v[202:205], v[18:21]
	v_mfma_f32_16x16x32_bf16 v[10:13], v[178:181], v[202:205], v[10:13]
	v_mfma_f32_16x16x32_bf16 v[6:9], v[170:173], v[210:213], v[6:9]
	v_mfma_f32_16x16x32_bf16 v[2:5], v[178:181], v[210:213], v[2:5]
	v_mfma_f32_16x16x32_bf16 v[50:53], v[174:177], v[190:193], v[50:53]
	v_mfma_f32_16x16x32_bf16 v[42:45], v[182:185], v[190:193], v[42:45]
	v_mfma_f32_16x16x32_bf16 v[34:37], v[174:177], v[198:201], v[34:37]
	v_mfma_f32_16x16x32_bf16 v[26:29], v[182:185], v[198:201], v[26:29]
	v_mfma_f32_16x16x32_bf16 v[18:21], v[174:177], v[206:209], v[18:21]
	v_mfma_f32_16x16x32_bf16 v[10:13], v[182:185], v[206:209], v[10:13]
	v_mfma_f32_16x16x32_bf16 v[6:9], v[174:177], v[214:217], v[6:9]
	v_mfma_f32_16x16x32_bf16 v[2:5], v[182:185], v[214:217], v[2:5]
	s_add_i32 s64, s64, 2
	s_add_u32 s36, s36, 0x100
	s_addc_u32 s37, s37, 0
	s_add_u32 s62, s62, 0x100
	s_addc_u32 s63, s63, 0
	s_cmp_gt_u32 s64, 61
	s_setprio 0
	s_barrier
	s_cbranch_scc0 .LBB0_1211
	s_and_b64 vcc, exec, s[12:13]
	s_cbranch_vccz .LBB0_1214
	s_barrier

.LBB0_1337:
	ds_read_b128 v[154:157], v151
	ds_read_b128 v[158:161], v151 offset:1024
	ds_read_b128 v[162:165], v151 offset:2048
	ds_read_b128 v[166:169], v151 offset:3072
	ds_read_b128 v[170:173], v152
	ds_read_b128 v[174:177], v152 offset:1024
	ds_read_b128 v[178:181], v152 offset:2048
	ds_read_b128 v[182:185], v152 offset:3072
	s_add_u32 s26, s24, 0xfff00080
	s_addc_u32 s27, s25, -1
	s_cmp_eq_u32 s53, 60
	s_cselect_b32 s29, s17, s27
	s_cselect_b32 s28, s49, s26
	s_cselect_b32 s27, s13, s52
	s_cselect_b32 s26, s50, s51
	v_lshl_add_u64 v[146:147], s[24:25], 0, v[138:139]
	s_add_i32 m0, s23, 0xc000
	ds_read_b128 v[186:189], v153
	ds_read_b128 v[190:193], v153 offset:1024
	ds_read_b128 v[194:197], v153 offset:2048
	ds_read_b128 v[198:201], v153 offset:3072
	ds_read_b128 v[202:205], v153 offset:4096
	ds_read_b128 v[206:209], v153 offset:5120
	ds_read_b128 v[210:213], v153 offset:6144
	ds_read_b128 v[214:217], v153 offset:7168
	global_load_lds_dwordx4 v[146:147], off
	v_lshl_add_u64 v[146:147], s[24:25], 0, v[140:141]
	s_add_i32 m0, s23, 0xe000
	s_nop 0
	global_load_lds_dwordx4 v[146:147], off
	s_waitcnt vmcnt(8)
	s_waitcnt lgkmcnt(0)
	s_barrier
	s_setprio 1
	s_waitcnt lgkmcnt(0)
	v_mfma_f32_16x16x32_bf16 v[126:129], v[154:157], v[186:189], v[126:129]
	v_mfma_f32_16x16x32_bf16 v[122:125], v[162:165], v[186:189], v[122:125]
	v_mfma_f32_16x16x32_bf16 v[110:113], v[154:157], v[194:197], v[110:113]
	v_mfma_f32_16x16x32_bf16 v[106:109], v[162:165], v[194:197], v[106:109]
	v_mfma_f32_16x16x32_bf16 v[94:97], v[154:157], v[202:205], v[94:97]
	v_mfma_f32_16x16x32_bf16 v[90:93], v[162:165], v[202:205], v[90:93]
	v_mfma_f32_16x16x32_bf16 v[78:81], v[154:157], v[210:213], v[78:81]
	v_mfma_f32_16x16x32_bf16 v[74:77], v[162:165], v[210:213], v[74:77]
	v_mfma_f32_16x16x32_bf16 v[126:129], v[158:161], v[190:193], v[126:129]
	v_mfma_f32_16x16x32_bf16 v[122:125], v[166:169], v[190:193], v[122:125]
	v_mfma_f32_16x16x32_bf16 v[110:113], v[158:161], v[198:201], v[110:113]
	v_mfma_f32_16x16x32_bf16 v[106:109], v[166:169], v[198:201], v[106:109]
	v_mfma_f32_16x16x32_bf16 v[94:97], v[158:161], v[206:209], v[94:97]
	v_mfma_f32_16x16x32_bf16 v[90:93], v[166:169], v[206:209], v[90:93]
	v_mfma_f32_16x16x32_bf16 v[78:81], v[158:161], v[214:217], v[78:81]
	v_mfma_f32_16x16x32_bf16 v[74:77], v[166:169], v[214:217], v[74:77]
	s_setprio 0
	s_setprio 1
	v_mfma_f32_16x16x32_bf16 v[118:121], v[170:173], v[186:189], v[118:121]
	v_mfma_f32_16x16x32_bf16 v[114:117], v[178:181], v[186:189], v[114:117]
	v_mfma_f32_16x16x32_bf16 v[102:105], v[170:173], v[194:197], v[102:105]
	v_mfma_f32_16x16x32_bf16 v[98:101], v[178:181], v[194:197], v[98:101]
	v_mfma_f32_16x16x32_bf16 v[86:89], v[170:173], v[202:205], v[86:89]
	v_mfma_f32_16x16x32_bf16 v[82:85], v[178:181], v[202:205], v[82:85]
	v_mfma_f32_16x16x32_bf16 v[70:73], v[170:173], v[210:213], v[70:73]
	v_mfma_f32_16x16x32_bf16 v[66:69], v[178:181], v[210:213], v[66:69]
	v_mfma_f32_16x16x32_bf16 v[118:121], v[174:177], v[190:193], v[118:121]
	v_mfma_f32_16x16x32_bf16 v[114:117], v[182:185], v[190:193], v[114:117]
	v_mfma_f32_16x16x32_bf16 v[102:105], v[174:177], v[198:201], v[102:105]
	v_mfma_f32_16x16x32_bf16 v[98:101], v[182:185], v[198:201], v[98:101]
	v_mfma_f32_16x16x32_bf16 v[86:89], v[174:177], v[206:209], v[86:89]
	v_mfma_f32_16x16x32_bf16 v[82:85], v[182:185], v[206:209], v[82:85]
	v_mfma_f32_16x16x32_bf16 v[70:73], v[174:177], v[214:217], v[70:73]
	v_mfma_f32_16x16x32_bf16 v[66:69], v[182:185], v[214:217], v[66:69]
	s_setprio 0
	s_barrier
	s_add_i32 s54, s45, s15
	v_lshl_add_u64 v[146:147], s[26:27], 0, v[134:135]
	s_mov_b32 m0, s54
	ds_read_b128 v[186:189], v153 offset:16384
	ds_read_b128 v[190:193], v153 offset:17408
	ds_read_b128 v[194:197], v153 offset:18432
	ds_read_b128 v[198:201], v153 offset:19456
	ds_read_b128 v[202:205], v153 offset:20480
	ds_read_b128 v[206:209], v153 offset:21504
	ds_read_b128 v[210:213], v153 offset:22528
	ds_read_b128 v[214:217], v153 offset:23552
	global_load_lds_dwordx4 v[146:147], off
	s_add_i32 m0, s54, 0x2000
	s_add_u32 s54, s26, 0x100000
	v_lshl_add_u64 v[218:219], s[26:27], 0, v[130:131]
	s_addc_u32 s55, s27, 0
	s_add_i32 s56, s46, s15
	global_load_lds_dwordx4 v[218:219], off
	v_lshl_add_u64 v[220:221], s[54:55], 0, v[134:135]
	s_mov_b32 m0, s56
	v_lshl_add_u64 v[222:223], s[28:29], 0, v[132:133]
	global_load_lds_dwordx4 v[220:221], off
	v_lshl_add_u64 v[220:221], s[54:55], 0, v[130:131]
	s_add_i32 m0, s56, 0x2000
	s_nop 0
	global_load_lds_dwordx4 v[220:221], off
	v_lshl_add_u64 v[220:221], s[28:29], 0, v[136:137]
	s_mov_b32 m0, s23
	s_nop 0
	global_load_lds_dwordx4 v[220:221], off
	s_mov_b32 m0, s36
	s_nop 0
	global_load_lds_dwordx4 v[222:223], off
	s_waitcnt vmcnt(8)
	s_waitcnt lgkmcnt(0)
	s_barrier
	s_setprio 1
	s_waitcnt lgkmcnt(0)
	v_mfma_f32_16x16x32_bf16 v[62:65], v[154:157], v[186:189], v[62:65]
	v_mfma_f32_16x16x32_bf16 v[58:61], v[162:165], v[186:189], v[58:61]
	v_mfma_f32_16x16x32_bf16 v[46:49], v[154:157], v[194:197], v[46:49]
	v_mfma_f32_16x16x32_bf16 v[42:45], v[162:165], v[194:197], v[42:45]
	v_mfma_f32_16x16x32_bf16 v[30:33], v[154:157], v[202:205], v[30:33]
	v_mfma_f32_16x16x32_bf16 v[26:29], v[162:165], v[202:205], v[26:29]
	v_mfma_f32_16x16x32_bf16 v[14:17], v[154:157], v[210:213], v[14:17]
	v_mfma_f32_16x16x32_bf16 v[10:13], v[162:165], v[210:213], v[10:13]
	v_mfma_f32_16x16x32_bf16 v[62:65], v[158:161], v[190:193], v[62:65]
	v_mfma_f32_16x16x32_bf16 v[58:61], v[166:169], v[190:193], v[58:61]
	v_mfma_f32_16x16x32_bf16 v[46:49], v[158:161], v[198:201], v[46:49]
	v_mfma_f32_16x16x32_bf16 v[42:45], v[166:169], v[198:201], v[42:45]
	v_mfma_f32_16x16x32_bf16 v[30:33], v[158:161], v[206:209], v[30:33]
	v_mfma_f32_16x16x32_bf16 v[26:29], v[166:169], v[206:209], v[26:29]
	v_mfma_f32_16x16x32_bf16 v[14:17], v[158:161], v[214:217], v[14:17]
	v_mfma_f32_16x16x32_bf16 v[10:13], v[166:169], v[214:217], v[10:13]
	s_setprio 0
	s_setprio 1
	v_mfma_f32_16x16x32_bf16 v[54:57], v[170:173], v[186:189], v[54:57]
	v_mfma_f32_16x16x32_bf16 v[50:53], v[178:181], v[186:189], v[50:53]
	v_mfma_f32_16x16x32_bf16 v[38:41], v[170:173], v[194:197], v[38:41]
	v_mfma_f32_16x16x32_bf16 v[34:37], v[178:181], v[194:197], v[34:37]
	v_mfma_f32_16x16x32_bf16 v[22:25], v[170:173], v[202:205], v[22:25]
	v_mfma_f32_16x16x32_bf16 v[18:21], v[178:181], v[202:205], v[18:21]
	v_mfma_f32_16x16x32_bf16 v[6:9], v[170:173], v[210:213], v[6:9]
	v_mfma_f32_16x16x32_bf16 v[2:5], v[178:181], v[210:213], v[2:5]
	v_mfma_f32_16x16x32_bf16 v[54:57], v[174:177], v[190:193], v[54:57]
	v_mfma_f32_16x16x32_bf16 v[50:53], v[182:185], v[190:193], v[50:53]
	v_mfma_f32_16x16x32_bf16 v[38:41], v[174:177], v[198:201], v[38:41]
	v_mfma_f32_16x16x32_bf16 v[34:37], v[182:185], v[198:201], v[34:37]
	v_mfma_f32_16x16x32_bf16 v[22:25], v[174:177], v[206:209], v[22:25]
	v_mfma_f32_16x16x32_bf16 v[18:21], v[182:185], v[206:209], v[18:21]
	v_mfma_f32_16x16x32_bf16 v[6:9], v[174:177], v[214:217], v[6:9]
	v_mfma_f32_16x16x32_bf16 v[2:5], v[182:185], v[214:217], v[2:5]
	s_setprio 0
	s_barrier
	s_add_i32 s54, 0, 0x18000
	s_add_i32 s55, 0, 0x1c000
	v_add_u32_e32 v166, s54, v149
	v_add_u32_e32 v182, s55, v149
	ds_read_b128 v[154:157], v166
	ds_read_b128 v[158:161], v166 offset:1024
	ds_read_b128 v[162:165], v166 offset:2048
	ds_read_b128 v[166:169], v166 offset:3072
	ds_read_b128 v[170:173], v182
	ds_read_b128 v[174:177], v182 offset:1024
	ds_read_b128 v[178:181], v182 offset:2048
	ds_read_b128 v[182:185], v182 offset:3072
	s_add_u32 s28, s28, 0x100000
	s_addc_u32 s29, s29, 0
	s_mov_b32 m0, s37
	v_lshl_add_u64 v[224:225], s[28:29], 0, v[136:137]
	ds_read_b128 v[186:189], v153 offset:32768
	ds_read_b128 v[190:193], v153 offset:33792
	ds_read_b128 v[194:197], v153 offset:34816
	ds_read_b128 v[198:201], v153 offset:35840
	ds_read_b128 v[202:205], v153 offset:36864
	ds_read_b128 v[206:209], v153 offset:37888
	ds_read_b128 v[210:213], v153 offset:38912
	ds_read_b128 v[214:217], v153 offset:39936
	global_load_lds_dwordx4 v[224:225], off
	v_lshl_add_u64 v[224:225], s[28:29], 0, v[132:133]
	s_mov_b32 m0, s40
	s_nop 0
	global_load_lds_dwordx4 v[224:225], off
	s_waitcnt vmcnt(8)
	s_waitcnt lgkmcnt(0)
	s_barrier
	s_setprio 1
	s_waitcnt lgkmcnt(0)
	v_mfma_f32_16x16x32_bf16 v[126:129], v[154:157], v[186:189], v[126:129]
	v_mfma_f32_16x16x32_bf16 v[122:125], v[162:165], v[186:189], v[122:125]
	v_mfma_f32_16x16x32_bf16 v[110:113], v[154:157], v[194:197], v[110:113]
	v_mfma_f32_16x16x32_bf16 v[106:109], v[162:165], v[194:197], v[106:109]
	v_mfma_f32_16x16x32_bf16 v[94:97], v[154:157], v[202:205], v[94:97]
	v_mfma_f32_16x16x32_bf16 v[90:93], v[162:165], v[202:205], v[90:93]
	v_mfma_f32_16x16x32_bf16 v[78:81], v[154:157], v[210:213], v[78:81]
	v_mfma_f32_16x16x32_bf16 v[74:77], v[162:165], v[210:213], v[74:77]
	v_mfma_f32_16x16x32_bf16 v[126:129], v[158:161], v[190:193], v[126:129]
	v_mfma_f32_16x16x32_bf16 v[122:125], v[166:169], v[190:193], v[122:125]
	v_mfma_f32_16x16x32_bf16 v[110:113], v[158:161], v[198:201], v[110:113]
	v_mfma_f32_16x16x32_bf16 v[106:109], v[166:169], v[198:201], v[106:109]
	v_mfma_f32_16x16x32_bf16 v[94:97], v[158:161], v[206:209], v[94:97]
	v_mfma_f32_16x16x32_bf16 v[90:93], v[166:169], v[206:209], v[90:93]
	v_mfma_f32_16x16x32_bf16 v[78:81], v[158:161], v[214:217], v[78:81]
	v_mfma_f32_16x16x32_bf16 v[74:77], v[166:169], v[214:217], v[74:77]
	s_setprio 0
	s_setprio 1
	v_mfma_f32_16x16x32_bf16 v[118:121], v[170:173], v[186:189], v[118:121]
	v_mfma_f32_16x16x32_bf16 v[114:117], v[178:181], v[186:189], v[114:117]
	v_mfma_f32_16x16x32_bf16 v[102:105], v[170:173], v[194:197], v[102:105]
	v_mfma_f32_16x16x32_bf16 v[98:101], v[178:181], v[194:197], v[98:101]
	v_mfma_f32_16x16x32_bf16 v[86:89], v[170:173], v[202:205], v[86:89]
	v_mfma_f32_16x16x32_bf16 v[82:85], v[178:181], v[202:205], v[82:85]
	v_mfma_f32_16x16x32_bf16 v[70:73], v[170:173], v[210:213], v[70:73]
	v_mfma_f32_16x16x32_bf16 v[66:69], v[178:181], v[210:213], v[66:69]
	v_mfma_f32_16x16x32_bf16 v[118:121], v[174:177], v[190:193], v[118:121]
	v_mfma_f32_16x16x32_bf16 v[114:117], v[182:185], v[190:193], v[114:117]
	v_mfma_f32_16x16x32_bf16 v[102:105], v[174:177], v[198:201], v[102:105]
	v_mfma_f32_16x16x32_bf16 v[98:101], v[182:185], v[198:201], v[98:101]
	v_mfma_f32_16x16x32_bf16 v[86:89], v[174:177], v[206:209], v[86:89]
	v_mfma_f32_16x16x32_bf16 v[82:85], v[182:185], v[206:209], v[82:85]
	v_mfma_f32_16x16x32_bf16 v[70:73], v[174:177], v[214:217], v[70:73]
	v_mfma_f32_16x16x32_bf16 v[66:69], v[182:185], v[214:217], v[66:69]
	s_setprio 0
	s_barrier
	s_add_i32 s28, s54, s15
	v_lshl_add_u64 v[146:147], v[146:147], 0, s[8:9]
	s_mov_b32 m0, s28
	ds_read_b128 v[186:189], v153 offset:49152
	ds_read_b128 v[190:193], v153 offset:50176
	ds_read_b128 v[194:197], v153 offset:51200
	ds_read_b128 v[198:201], v153 offset:52224
	ds_read_b128 v[202:205], v153 offset:53248
	ds_read_b128 v[206:209], v153 offset:54272
	ds_read_b128 v[210:213], v153 offset:55296
	ds_read_b128 v[214:217], v153 offset:56320
	global_load_lds_dwordx4 v[146:147], off
	s_add_i32 m0, s28, 0x2000
	s_add_u32 s26, s26, 0x100080
	v_lshl_add_u64 v[146:147], v[218:219], 0, s[8:9]
	s_addc_u32 s27, s27, 0
	s_add_i32 s28, s55, s15
	global_load_lds_dwordx4 v[146:147], off
	v_lshl_add_u64 v[146:147], s[26:27], 0, v[134:135]
	s_mov_b32 m0, s28
	s_nop 0
	global_load_lds_dwordx4 v[146:147], off
	v_lshl_add_u64 v[146:147], s[26:27], 0, v[130:131]
	s_add_i32 m0, s28, 0x2000
	s_nop 0
	global_load_lds_dwordx4 v[146:147], off
	v_lshl_add_u64 v[146:147], v[220:221], 0, s[8:9]
	s_mov_b32 m0, s42
	s_nop 0
	global_load_lds_dwordx4 v[146:147], off
	v_lshl_add_u64 v[146:147], v[222:223], 0, s[8:9]
	s_mov_b32 m0, s43
	s_nop 0
	global_load_lds_dwordx4 v[146:147], off
	s_waitcnt vmcnt(8)
	s_waitcnt lgkmcnt(0)
	s_barrier
	s_setprio 1
	s_waitcnt lgkmcnt(0)
	v_mfma_f32_16x16x32_bf16 v[62:65], v[154:157], v[186:189], v[62:65]
	v_mfma_f32_16x16x32_bf16 v[58:61], v[162:165], v[186:189], v[58:61]
	v_mfma_f32_16x16x32_bf16 v[46:49], v[154:157], v[194:197], v[46:49]
	v_mfma_f32_16x16x32_bf16 v[42:45], v[162:165], v[194:197], v[42:45]
	v_mfma_f32_16x16x32_bf16 v[30:33], v[154:157], v[202:205], v[30:33]
	v_mfma_f32_16x16x32_bf16 v[26:29], v[162:165], v[202:205], v[26:29]
	v_mfma_f32_16x16x32_bf16 v[14:17], v[154:157], v[210:213], v[14:17]
	v_mfma_f32_16x16x32_bf16 v[10:13], v[162:165], v[210:213], v[10:13]
	v_mfma_f32_16x16x32_bf16 v[62:65], v[158:161], v[190:193], v[62:65]
	v_mfma_f32_16x16x32_bf16 v[58:61], v[166:169], v[190:193], v[58:61]
	v_mfma_f32_16x16x32_bf16 v[46:49], v[158:161], v[198:201], v[46:49]
	v_mfma_f32_16x16x32_bf16 v[42:45], v[166:169], v[198:201], v[42:45]
	v_mfma_f32_16x16x32_bf16 v[30:33], v[158:161], v[206:209], v[30:33]
	v_mfma_f32_16x16x32_bf16 v[26:29], v[166:169], v[206:209], v[26:29]
	v_mfma_f32_16x16x32_bf16 v[14:17], v[158:161], v[214:217], v[14:17]
	v_mfma_f32_16x16x32_bf16 v[10:13], v[166:169], v[214:217], v[10:13]
	s_setprio 0
	s_setprio 1
	v_mfma_f32_16x16x32_bf16 v[54:57], v[170:173], v[186:189], v[54:57]
	v_mfma_f32_16x16x32_bf16 v[50:53], v[178:181], v[186:189], v[50:53]
	v_mfma_f32_16x16x32_bf16 v[38:41], v[170:173], v[194:197], v[38:41]
	v_mfma_f32_16x16x32_bf16 v[34:37], v[178:181], v[194:197], v[34:37]
	v_mfma_f32_16x16x32_bf16 v[22:25], v[170:173], v[202:205], v[22:25]
	v_mfma_f32_16x16x32_bf16 v[18:21], v[178:181], v[202:205], v[18:21]
	v_mfma_f32_16x16x32_bf16 v[6:9], v[170:173], v[210:213], v[6:9]
	v_mfma_f32_16x16x32_bf16 v[2:5], v[178:181], v[210:213], v[2:5]
	v_mfma_f32_16x16x32_bf16 v[54:57], v[174:177], v[190:193], v[54:57]
	v_mfma_f32_16x16x32_bf16 v[50:53], v[182:185], v[190:193], v[50:53]
	v_mfma_f32_16x16x32_bf16 v[38:41], v[174:177], v[198:201], v[38:41]
	v_mfma_f32_16x16x32_bf16 v[34:37], v[182:185], v[198:201], v[34:37]
	v_mfma_f32_16x16x32_bf16 v[22:25], v[174:177], v[206:209], v[22:25]
	v_mfma_f32_16x16x32_bf16 v[18:21], v[182:185], v[206:209], v[18:21]
	v_mfma_f32_16x16x32_bf16 v[6:9], v[174:177], v[214:217], v[6:9]
	v_mfma_f32_16x16x32_bf16 v[2:5], v[182:185], v[214:217], v[2:5]
	s_add_i32 s53, s53, 2
	s_add_u32 s24, s24, 0x100
	s_addc_u32 s25, s25, 0
	s_add_u32 s51, s51, 0x100
	s_addc_u32 s52, s52, 0
	s_cmp_gt_u32 s53, 61
	s_setprio 0
	s_barrier
	s_cbranch_scc0 .LBB0_1337
	s_and_b64 vcc, exec, s[10:11]
	s_cbranch_vccz .LBB0_1340
	s_barrier

.LBB0_1434:
	ds_read_b128 v[154:157], v150
	ds_read_b128 v[158:161], v150 offset:1024
	ds_read_b128 v[162:165], v150 offset:2048
	ds_read_b128 v[166:169], v150 offset:3072
	ds_read_b128 v[170:173], v151
	ds_read_b128 v[174:177], v151 offset:1024
	ds_read_b128 v[178:181], v151 offset:2048
	ds_read_b128 v[182:185], v151 offset:3072
	s_add_u32 s30, s28, 0x100
	s_addc_u32 s31, s29, 0
	s_cmpk_eq_i32 s66, 0xa8
	s_cselect_b32 s41, s5, s31
	s_cselect_b32 s40, s4, s30
	s_cselect_b32 s37, s27, s65
	s_cselect_b32 s36, s26, s64
	v_lshl_add_u64 v[146:147], s[28:29], 0, v[138:139]
	s_add_i32 m0, s15, 0xc000
	ds_read_b128 v[186:189], v152
	ds_read_b128 v[190:193], v152 offset:1024
	ds_read_b128 v[194:197], v152 offset:2048
	ds_read_b128 v[198:201], v152 offset:3072
	ds_read_b128 v[202:205], v152 offset:4096
	ds_read_b128 v[206:209], v152 offset:5120
	ds_read_b128 v[210:213], v152 offset:6144
	ds_read_b128 v[214:217], v152 offset:7168
	global_load_lds_dwordx4 v[146:147], off
	v_lshl_add_u64 v[146:147], s[28:29], 0, v[140:141]
	s_add_i32 m0, s15, 0xe000
	s_nop 0
	global_load_lds_dwordx4 v[146:147], off
	s_waitcnt vmcnt(8)
	s_waitcnt lgkmcnt(0)
	s_barrier
	s_setprio 1
	s_waitcnt lgkmcnt(0)
	v_mfma_f32_16x16x32_bf16 v[126:129], v[154:157], v[186:189], v[126:129]
	v_mfma_f32_16x16x32_bf16 v[122:125], v[162:165], v[186:189], v[122:125]
	v_mfma_f32_16x16x32_bf16 v[118:121], v[154:157], v[194:197], v[118:121]
	v_mfma_f32_16x16x32_bf16 v[110:113], v[162:165], v[194:197], v[110:113]
	v_mfma_f32_16x16x32_bf16 v[102:105], v[154:157], v[202:205], v[102:105]
	v_mfma_f32_16x16x32_bf16 v[94:97], v[162:165], v[202:205], v[94:97]
	v_mfma_f32_16x16x32_bf16 v[86:89], v[154:157], v[210:213], v[86:89]
	v_mfma_f32_16x16x32_bf16 v[78:81], v[162:165], v[210:213], v[78:81]
	v_mfma_f32_16x16x32_bf16 v[126:129], v[158:161], v[190:193], v[126:129]
	v_mfma_f32_16x16x32_bf16 v[122:125], v[166:169], v[190:193], v[122:125]
	v_mfma_f32_16x16x32_bf16 v[118:121], v[158:161], v[198:201], v[118:121]
	v_mfma_f32_16x16x32_bf16 v[110:113], v[166:169], v[198:201], v[110:113]
	v_mfma_f32_16x16x32_bf16 v[102:105], v[158:161], v[206:209], v[102:105]
	v_mfma_f32_16x16x32_bf16 v[94:97], v[166:169], v[206:209], v[94:97]
	v_mfma_f32_16x16x32_bf16 v[86:89], v[158:161], v[214:217], v[86:89]
	v_mfma_f32_16x16x32_bf16 v[78:81], v[166:169], v[214:217], v[78:81]
	s_setprio 0
	s_setprio 1
	v_mfma_f32_16x16x32_bf16 v[114:117], v[170:173], v[186:189], v[114:117]
	v_mfma_f32_16x16x32_bf16 v[106:109], v[178:181], v[186:189], v[106:109]
	v_mfma_f32_16x16x32_bf16 v[98:101], v[170:173], v[194:197], v[98:101]
	v_mfma_f32_16x16x32_bf16 v[90:93], v[178:181], v[194:197], v[90:93]
	v_mfma_f32_16x16x32_bf16 v[82:85], v[170:173], v[202:205], v[82:85]
	v_mfma_f32_16x16x32_bf16 v[74:77], v[178:181], v[202:205], v[74:77]
	v_mfma_f32_16x16x32_bf16 v[70:73], v[170:173], v[210:213], v[70:73]
	v_mfma_f32_16x16x32_bf16 v[66:69], v[178:181], v[210:213], v[66:69]
	v_mfma_f32_16x16x32_bf16 v[114:117], v[174:177], v[190:193], v[114:117]
	v_mfma_f32_16x16x32_bf16 v[106:109], v[182:185], v[190:193], v[106:109]
	v_mfma_f32_16x16x32_bf16 v[98:101], v[174:177], v[198:201], v[98:101]
	v_mfma_f32_16x16x32_bf16 v[90:93], v[182:185], v[198:201], v[90:93]
	v_mfma_f32_16x16x32_bf16 v[82:85], v[174:177], v[206:209], v[82:85]
	v_mfma_f32_16x16x32_bf16 v[74:77], v[182:185], v[206:209], v[74:77]
	v_mfma_f32_16x16x32_bf16 v[70:73], v[174:177], v[214:217], v[70:73]
	v_mfma_f32_16x16x32_bf16 v[66:69], v[182:185], v[214:217], v[66:69]
	s_setprio 0
	s_barrier
	s_add_i32 s28, s52, s3
	v_lshl_add_u64 v[146:147], s[36:37], 0, v[132:133]
	s_mov_b32 m0, s28
	ds_read_b128 v[186:189], v152 offset:16384
	ds_read_b128 v[190:193], v152 offset:17408
	ds_read_b128 v[194:197], v152 offset:18432
	ds_read_b128 v[198:201], v152 offset:19456
	ds_read_b128 v[202:205], v152 offset:20480
	ds_read_b128 v[206:209], v152 offset:21504
	ds_read_b128 v[210:213], v152 offset:22528
	ds_read_b128 v[214:217], v152 offset:23552
	global_load_lds_dwordx4 v[146:147], off
	s_add_i32 m0, s28, 0x2000
	s_add_u32 s28, s36, 0x2b0000
	v_lshl_add_u64 v[218:219], s[36:37], 0, v[136:137]
	s_addc_u32 s29, s37, 0
	s_add_i32 s67, s53, s3
	global_load_lds_dwordx4 v[218:219], off
	v_lshl_add_u64 v[220:221], s[28:29], 0, v[132:133]
	s_mov_b32 m0, s67
	v_lshl_add_u64 v[222:223], s[40:41], 0, v[134:135]
	global_load_lds_dwordx4 v[220:221], off
	v_lshl_add_u64 v[220:221], s[28:29], 0, v[136:137]
	s_add_i32 m0, s67, 0x2000
	s_nop 0
	global_load_lds_dwordx4 v[220:221], off
	v_lshl_add_u64 v[220:221], s[40:41], 0, v[130:131]
	s_mov_b32 m0, s15
	s_nop 0
	global_load_lds_dwordx4 v[220:221], off
	s_mov_b32 m0, s42
	s_nop 0
	global_load_lds_dwordx4 v[222:223], off
	s_waitcnt vmcnt(8)
	s_waitcnt lgkmcnt(0)
	s_barrier
	s_setprio 1
	s_waitcnt lgkmcnt(0)
	v_mfma_f32_16x16x32_bf16 v[62:65], v[154:157], v[186:189], v[62:65]
	v_mfma_f32_16x16x32_bf16 v[58:61], v[162:165], v[186:189], v[58:61]
	v_mfma_f32_16x16x32_bf16 v[54:57], v[154:157], v[194:197], v[54:57]
	v_mfma_f32_16x16x32_bf16 v[46:49], v[162:165], v[194:197], v[46:49]
	v_mfma_f32_16x16x32_bf16 v[38:41], v[154:157], v[202:205], v[38:41]
	v_mfma_f32_16x16x32_bf16 v[30:33], v[162:165], v[202:205], v[30:33]
	v_mfma_f32_16x16x32_bf16 v[22:25], v[154:157], v[210:213], v[22:25]
	v_mfma_f32_16x16x32_bf16 v[14:17], v[162:165], v[210:213], v[14:17]
	v_mfma_f32_16x16x32_bf16 v[62:65], v[158:161], v[190:193], v[62:65]
	v_mfma_f32_16x16x32_bf16 v[58:61], v[166:169], v[190:193], v[58:61]
	v_mfma_f32_16x16x32_bf16 v[54:57], v[158:161], v[198:201], v[54:57]
	v_mfma_f32_16x16x32_bf16 v[46:49], v[166:169], v[198:201], v[46:49]
	v_mfma_f32_16x16x32_bf16 v[38:41], v[158:161], v[206:209], v[38:41]
	v_mfma_f32_16x16x32_bf16 v[30:33], v[166:169], v[206:209], v[30:33]
	v_mfma_f32_16x16x32_bf16 v[22:25], v[158:161], v[214:217], v[22:25]
	v_mfma_f32_16x16x32_bf16 v[14:17], v[166:169], v[214:217], v[14:17]
	s_setprio 0
	s_setprio 1
	v_mfma_f32_16x16x32_bf16 v[50:53], v[170:173], v[186:189], v[50:53]
	v_mfma_f32_16x16x32_bf16 v[42:45], v[178:181], v[186:189], v[42:45]
	v_mfma_f32_16x16x32_bf16 v[34:37], v[170:173], v[194:197], v[34:37]
	v_mfma_f32_16x16x32_bf16 v[26:29], v[178:181], v[194:197], v[26:29]
	v_mfma_f32_16x16x32_bf16 v[18:21], v[170:173], v[202:205], v[18:21]
	v_mfma_f32_16x16x32_bf16 v[10:13], v[178:181], v[202:205], v[10:13]
	v_mfma_f32_16x16x32_bf16 v[6:9], v[170:173], v[210:213], v[6:9]
	v_mfma_f32_16x16x32_bf16 v[2:5], v[178:181], v[210:213], v[2:5]
	v_mfma_f32_16x16x32_bf16 v[50:53], v[174:177], v[190:193], v[50:53]
	v_mfma_f32_16x16x32_bf16 v[42:45], v[182:185], v[190:193], v[42:45]
	v_mfma_f32_16x16x32_bf16 v[34:37], v[174:177], v[198:201], v[34:37]
	v_mfma_f32_16x16x32_bf16 v[26:29], v[182:185], v[198:201], v[26:29]
	v_mfma_f32_16x16x32_bf16 v[18:21], v[174:177], v[206:209], v[18:21]
	v_mfma_f32_16x16x32_bf16 v[10:13], v[182:185], v[206:209], v[10:13]
	v_mfma_f32_16x16x32_bf16 v[6:9], v[174:177], v[214:217], v[6:9]
	v_mfma_f32_16x16x32_bf16 v[2:5], v[182:185], v[214:217], v[2:5]
	s_setprio 0
	s_barrier
	s_add_i32 s67, 0, 0x18000
	v_add_u32_e32 v153, s67, v148
	s_add_i32 s68, 0, 0x1c000
	ds_read_b128 v[154:157], v153
	ds_read_b128 v[158:161], v153 offset:1024
	ds_read_b128 v[162:165], v153 offset:2048
	ds_read_b128 v[166:169], v153 offset:3072
	v_add_u32_e32 v153, s68, v148
	ds_read_b128 v[170:173], v153
	ds_read_b128 v[174:177], v153 offset:1024
	ds_read_b128 v[178:181], v153 offset:2048
	ds_read_b128 v[182:185], v153 offset:3072
	s_add_u32 s28, s40, 0x2b0000
	s_addc_u32 s29, s41, 0
	s_mov_b32 m0, s43
	v_lshl_add_u64 v[224:225], s[28:29], 0, v[130:131]
	ds_read_b128 v[186:189], v152 offset:32768
	ds_read_b128 v[190:193], v152 offset:33792
	ds_read_b128 v[194:197], v152 offset:34816
	ds_read_b128 v[198:201], v152 offset:35840
	ds_read_b128 v[202:205], v152 offset:36864
	ds_read_b128 v[206:209], v152 offset:37888
	ds_read_b128 v[210:213], v152 offset:38912
	ds_read_b128 v[214:217], v152 offset:39936
	global_load_lds_dwordx4 v[224:225], off
	v_lshl_add_u64 v[224:225], s[28:29], 0, v[134:135]
	s_mov_b32 m0, s44
	s_nop 0
	global_load_lds_dwordx4 v[224:225], off
	s_waitcnt vmcnt(8)
	s_waitcnt lgkmcnt(0)
	s_barrier
	s_setprio 1
	s_waitcnt lgkmcnt(0)
	v_mfma_f32_16x16x32_bf16 v[126:129], v[154:157], v[186:189], v[126:129]
	v_mfma_f32_16x16x32_bf16 v[122:125], v[162:165], v[186:189], v[122:125]
	v_mfma_f32_16x16x32_bf16 v[118:121], v[154:157], v[194:197], v[118:121]
	v_mfma_f32_16x16x32_bf16 v[110:113], v[162:165], v[194:197], v[110:113]
	v_mfma_f32_16x16x32_bf16 v[102:105], v[154:157], v[202:205], v[102:105]
	v_mfma_f32_16x16x32_bf16 v[94:97], v[162:165], v[202:205], v[94:97]
	v_mfma_f32_16x16x32_bf16 v[86:89], v[154:157], v[210:213], v[86:89]
	v_mfma_f32_16x16x32_bf16 v[78:81], v[162:165], v[210:213], v[78:81]
	v_mfma_f32_16x16x32_bf16 v[126:129], v[158:161], v[190:193], v[126:129]
	v_mfma_f32_16x16x32_bf16 v[122:125], v[166:169], v[190:193], v[122:125]
	v_mfma_f32_16x16x32_bf16 v[118:121], v[158:161], v[198:201], v[118:121]
	v_mfma_f32_16x16x32_bf16 v[110:113], v[166:169], v[198:201], v[110:113]
	v_mfma_f32_16x16x32_bf16 v[102:105], v[158:161], v[206:209], v[102:105]
	v_mfma_f32_16x16x32_bf16 v[94:97], v[166:169], v[206:209], v[94:97]
	v_mfma_f32_16x16x32_bf16 v[86:89], v[158:161], v[214:217], v[86:89]
	v_mfma_f32_16x16x32_bf16 v[78:81], v[166:169], v[214:217], v[78:81]
	s_setprio 0
	s_setprio 1
	v_mfma_f32_16x16x32_bf16 v[114:117], v[170:173], v[186:189], v[114:117]
	v_mfma_f32_16x16x32_bf16 v[106:109], v[178:181], v[186:189], v[106:109]
	v_mfma_f32_16x16x32_bf16 v[98:101], v[170:173], v[194:197], v[98:101]
	v_mfma_f32_16x16x32_bf16 v[90:93], v[178:181], v[194:197], v[90:93]
	v_mfma_f32_16x16x32_bf16 v[82:85], v[170:173], v[202:205], v[82:85]
	v_mfma_f32_16x16x32_bf16 v[74:77], v[178:181], v[202:205], v[74:77]
	v_mfma_f32_16x16x32_bf16 v[70:73], v[170:173], v[210:213], v[70:73]
	v_mfma_f32_16x16x32_bf16 v[66:69], v[178:181], v[210:213], v[66:69]
	v_mfma_f32_16x16x32_bf16 v[114:117], v[174:177], v[190:193], v[114:117]
	v_mfma_f32_16x16x32_bf16 v[106:109], v[182:185], v[190:193], v[106:109]
	v_mfma_f32_16x16x32_bf16 v[98:101], v[174:177], v[198:201], v[98:101]
	v_mfma_f32_16x16x32_bf16 v[90:93], v[182:185], v[198:201], v[90:93]
	v_mfma_f32_16x16x32_bf16 v[82:85], v[174:177], v[206:209], v[82:85]
	v_mfma_f32_16x16x32_bf16 v[74:77], v[182:185], v[206:209], v[74:77]
	v_mfma_f32_16x16x32_bf16 v[70:73], v[174:177], v[214:217], v[70:73]
	v_mfma_f32_16x16x32_bf16 v[66:69], v[182:185], v[214:217], v[66:69]
	s_setprio 0
	s_barrier
	s_add_i32 s28, s67, s3
	v_lshl_add_u64 v[146:147], v[146:147], 0, s[12:13]
	s_mov_b32 m0, s28
	ds_read_b128 v[186:189], v152 offset:49152
	ds_read_b128 v[190:193], v152 offset:50176
	ds_read_b128 v[194:197], v152 offset:51200
	ds_read_b128 v[198:201], v152 offset:52224
	ds_read_b128 v[202:205], v152 offset:53248
	ds_read_b128 v[206:209], v152 offset:54272
	ds_read_b128 v[210:213], v152 offset:55296
	ds_read_b128 v[214:217], v152 offset:56320
	global_load_lds_dwordx4 v[146:147], off
	s_add_i32 m0, s28, 0x2000
	s_add_u32 s28, s36, 0x2b0080
	v_lshl_add_u64 v[146:147], v[218:219], 0, s[12:13]
	s_addc_u32 s29, s37, 0
	s_add_i32 s36, s68, s3
	global_load_lds_dwordx4 v[146:147], off
	v_lshl_add_u64 v[146:147], s[28:29], 0, v[132:133]
	s_mov_b32 m0, s36
	s_nop 0
	global_load_lds_dwordx4 v[146:147], off
	v_lshl_add_u64 v[146:147], s[28:29], 0, v[136:137]
	s_add_i32 m0, s36, 0x2000
	s_nop 0
	global_load_lds_dwordx4 v[146:147], off
	v_lshl_add_u64 v[146:147], v[220:221], 0, s[12:13]
	s_mov_b32 m0, s46
	s_nop 0
	global_load_lds_dwordx4 v[146:147], off
	v_lshl_add_u64 v[146:147], v[222:223], 0, s[12:13]
	s_mov_b32 m0, s47
	s_nop 0
	global_load_lds_dwordx4 v[146:147], off
	s_waitcnt vmcnt(8)
	s_waitcnt lgkmcnt(0)
	s_barrier
	s_setprio 1
	s_waitcnt lgkmcnt(0)
	v_mfma_f32_16x16x32_bf16 v[62:65], v[154:157], v[186:189], v[62:65]
	v_mfma_f32_16x16x32_bf16 v[58:61], v[162:165], v[186:189], v[58:61]
	v_mfma_f32_16x16x32_bf16 v[54:57], v[154:157], v[194:197], v[54:57]
	v_mfma_f32_16x16x32_bf16 v[46:49], v[162:165], v[194:197], v[46:49]
	v_mfma_f32_16x16x32_bf16 v[38:41], v[154:157], v[202:205], v[38:41]
	v_mfma_f32_16x16x32_bf16 v[30:33], v[162:165], v[202:205], v[30:33]
	v_mfma_f32_16x16x32_bf16 v[22:25], v[154:157], v[210:213], v[22:25]
	v_mfma_f32_16x16x32_bf16 v[14:17], v[162:165], v[210:213], v[14:17]
	v_mfma_f32_16x16x32_bf16 v[62:65], v[158:161], v[190:193], v[62:65]
	v_mfma_f32_16x16x32_bf16 v[58:61], v[166:169], v[190:193], v[58:61]
	v_mfma_f32_16x16x32_bf16 v[54:57], v[158:161], v[198:201], v[54:57]
	v_mfma_f32_16x16x32_bf16 v[46:49], v[166:169], v[198:201], v[46:49]
	v_mfma_f32_16x16x32_bf16 v[38:41], v[158:161], v[206:209], v[38:41]
	v_mfma_f32_16x16x32_bf16 v[30:33], v[166:169], v[206:209], v[30:33]
	v_mfma_f32_16x16x32_bf16 v[22:25], v[158:161], v[214:217], v[22:25]
	v_mfma_f32_16x16x32_bf16 v[14:17], v[166:169], v[214:217], v[14:17]
	s_setprio 0
	s_setprio 1
	v_mfma_f32_16x16x32_bf16 v[50:53], v[170:173], v[186:189], v[50:53]
	v_mfma_f32_16x16x32_bf16 v[42:45], v[178:181], v[186:189], v[42:45]
	v_mfma_f32_16x16x32_bf16 v[34:37], v[170:173], v[194:197], v[34:37]
	v_mfma_f32_16x16x32_bf16 v[26:29], v[178:181], v[194:197], v[26:29]
	v_mfma_f32_16x16x32_bf16 v[18:21], v[170:173], v[202:205], v[18:21]
	v_mfma_f32_16x16x32_bf16 v[10:13], v[178:181], v[202:205], v[10:13]
	v_mfma_f32_16x16x32_bf16 v[6:9], v[170:173], v[210:213], v[6:9]
	v_mfma_f32_16x16x32_bf16 v[2:5], v[178:181], v[210:213], v[2:5]
	v_mfma_f32_16x16x32_bf16 v[50:53], v[174:177], v[190:193], v[50:53]
	v_mfma_f32_16x16x32_bf16 v[42:45], v[182:185], v[190:193], v[42:45]
	v_mfma_f32_16x16x32_bf16 v[34:37], v[174:177], v[198:201], v[34:37]
	v_mfma_f32_16x16x32_bf16 v[26:29], v[182:185], v[198:201], v[26:29]
	v_mfma_f32_16x16x32_bf16 v[18:21], v[174:177], v[206:209], v[18:21]
	v_mfma_f32_16x16x32_bf16 v[10:13], v[182:185], v[206:209], v[10:13]
	v_mfma_f32_16x16x32_bf16 v[6:9], v[174:177], v[214:217], v[6:9]
	v_mfma_f32_16x16x32_bf16 v[2:5], v[182:185], v[214:217], v[2:5]
	s_add_i32 s66, s66, 2
	s_add_u32 s64, s64, 0x100
	s_addc_u32 s65, s65, 0
	s_cmpk_gt_u32 s66, 0xa9
	s_mov_b64 s[28:29], s[30:31]
	s_setprio 0
	s_barrier
	s_cbranch_scc0 .LBB0_1434
	s_and_b64 vcc, exec, s[16:17]
	s_cbranch_vccz .LBB0_1437
	s_barrier
